# dense loop with fewer issue slots: one K and one V base pointer with two per-lane offsets each, M0 set one gap ahead (no s_nop), fragment waits merged in pairs, V lookahead 6
# speedup vs baseline: 1.0010x; 1.0010x over previous
; __device__ __forceinline__ int v_st(int k, int c) { const int kk = (k & ~0xC) | ((k & 4) << 1) | ((k & 8) >> 1); return ((kk >> 3) * 4 + (c >> 5)) * 512 + ((kk & 7) * 32 + (c & 31)) * 2; }
; __device__ __forceinline__ int v_rd_base(int lane) { return ((lane & 3) << 3) | (((lane >> 2) & 3) << 6) | (((lane >> 4) & 1) << 5) | (((lane >> 5) & 1) << 8); }
;     ...
;   const int sr = tid >> 4, sc = (tid & 15) * 8, vst0 = v_st(sr, sc), vst1 = vst0 + 8192;
;   const int vb0 = (int)(uintptr_t)V_lds + v_rd_base(lane);
;   const int qrel = wid * QBLK + r32;
;   constexpr int SD = (MODE == 0) ? ATT_SD0 : 2;
;   struct { bf16x8 vs0, vs1, ks0, ks1; } sr_[SD];
;   const unsigned soff0 = (unsigned)(sr * (int)ldk + sc) * 2u, soff1 = soff0 + (unsigned)(32 * (int)ldk) * 2u;
;     ...
;   PLOAD(0); asm volatile("s_waitcnt vmcnt(0)" ::: "memory"); PWRITE(0); __syncthreads();
.LBB0_486:
	v_and_b32_e32 v64, 63, v218
	v_and_b32_e32 v65, 15, v64
	v_lshrrev_b32_e32 v66, 4, v64
	v_add_u32_e32 v67, 0, v66
	v_xor_b32_e32 v67, v67, v65
	v_lshlrev_b32_e32 v67, 4, v67
	v_lshl_or_b32 v172, v65, 8, v67
	v_add_u32_e32 v67, 4, v66
	v_xor_b32_e32 v67, v67, v65
	v_lshlrev_b32_e32 v67, 4, v67
	v_lshl_or_b32 v173, v65, 8, v67
	v_add_u32_e32 v67, 8, v66
	v_xor_b32_e32 v67, v67, v65
	v_lshlrev_b32_e32 v67, 4, v67
	v_lshl_or_b32 v174, v65, 8, v67
	v_add_u32_e32 v67, 12, v66
	v_xor_b32_e32 v67, v67, v65
	v_lshlrev_b32_e32 v67, 4, v67
	v_lshl_or_b32 v175, v65, 8, v67
	v_bfe_u32 v68, v64, 2, 2
	v_and_b32_e32 v69, 3, v64
	v_lshl_add_u32 v70, v66, 2, v68
	v_and_b32_e32 v71, 7, v70
	v_lshlrev_b32_e32 v70, 8, v70
	v_lshl_add_u32 v70, v69, 3, v70
	v_add_u32_e32 v70, 0x10000, v70
	v_xor_b32_e32 v72, 0, v71
	v_lshl_add_u32 v176, v72, 5, v70
	v_xor_b32_e32 v72, 1, v71
	v_lshl_add_u32 v177, v72, 5, v70
	v_xor_b32_e32 v72, 2, v71
	v_lshl_add_u32 v178, v72, 5, v70
	v_xor_b32_e32 v72, 3, v71
	v_lshl_add_u32 v179, v72, 5, v70
	v_xor_b32_e32 v72, 4, v71
	v_lshl_add_u32 v180, v72, 5, v70
	v_xor_b32_e32 v72, 5, v71
	v_lshl_add_u32 v182, v72, 5, v70
	v_xor_b32_e32 v72, 6, v71
	v_lshl_add_u32 v216, v72, 5, v70
	v_xor_b32_e32 v72, 7, v71
	v_lshl_add_u32 v217, v72, 5, v70
	v_lshrrev_b32_e32 v72, 4, v218
	v_and_b32_e32 v74, 15, v218
	v_and_b32_e32 v73, 15, v72
	v_xor_b32_e32 v73, v73, v74
	v_mul_u32_u24_e32 v75, 0x5400, v72
	v_lshl_add_u32 v183, v73, 4, v75
	v_and_b32_e32 v73, 7, v72
	v_lshlrev_b32_e32 v73, 1, v73
	v_xor_b32_e32 v73, v73, v74
	v_lshl_add_u32 v181, v73, 4, v75
	v_add_u32_e32 v181, 0x200, v181
	v_readfirstlane_b32 s32, v218
	s_nop 3
	s_lshr_b32 s32, s32, 6
	s_lshl_b32 s32, s32, 10
	v_add_u32_e32 v246, 0xa8000, v183
	v_add_u32_e32 v247, 0xa8000, v181
	s_sub_u32 s0, s98, 0x2a0000
	s_subb_u32 s1, s99, 0
	s_add_i32 m0, s32, 0x10000
	s_nop 0
	global_load_lds_dwordx4 v181, s[0:1]
	s_add_i32 m0, s32, 0x12000
	s_nop 0
	global_load_lds_dwordx4 v247, s[0:1]
	s_add_u32 s0, s0, 0x150000
	s_addc_u32 s1, s1, 0
	s_add_i32 m0, s32, 0x14000
	s_nop 0
	global_load_lds_dwordx4 v181, s[0:1]
	s_add_i32 m0, s32, 0x16000
	s_nop 0
	global_load_lds_dwordx4 v247, s[0:1]
	s_add_u32 s0, s0, 0x150000
	s_addc_u32 s1, s1, 0
	s_add_i32 m0, s32, 0x8000
	s_nop 0
	global_load_lds_dwordx4 v183, s[98:99]
	s_add_i32 m0, s32, 0xa000
	s_nop 0
	global_load_lds_dwordx4 v246, s[98:99]
	s_add_u32 s98, s98, 0x150000
	s_addc_u32 s99, s99, 0
	s_add_i32 m0, s32, 0xc000
	s_nop 0
	global_load_lds_dwordx4 v183, s[98:99]
	s_add_i32 m0, s32, 0xe000
	s_nop 0
	global_load_lds_dwordx4 v246, s[98:99]
	s_add_u32 s98, s98, 0x150000
	s_addc_u32 s99, s99, 0
	v_and_b32_e32 v67, 1, v66
	v_lshl_add_u32 v67, v67, 5, v65
	v_lshlrev_b32_e32 v68, 2, v67
	v_add_u32_e32 v69, 64, v68
	s_mov_b32 vcc_lo, 0
	s_mov_b32 vcc_hi, -1
	ds_bpermute_b32 v200, v68, v124
	ds_bpermute_b32 v201, v68, v120
	ds_bpermute_b32 v202, v68, v125
	ds_bpermute_b32 v203, v68, v121
	ds_bpermute_b32 v204, v68, v126
	ds_bpermute_b32 v205, v68, v122
	ds_bpermute_b32 v206, v68, v127
	ds_bpermute_b32 v207, v68, v123
	ds_bpermute_b32 v208, v68, v116
	ds_bpermute_b32 v209, v68, v112
	ds_bpermute_b32 v210, v68, v117
	ds_bpermute_b32 v211, v68, v113
	ds_bpermute_b32 v212, v68, v118
	ds_bpermute_b32 v213, v68, v114
	s_waitcnt lgkmcnt(0)
	v_cndmask_b32_e64 v128, v200, v201, vcc
	v_cndmask_b32_e64 v129, v202, v203, vcc
	v_cndmask_b32_e64 v130, v204, v205, vcc
	v_cndmask_b32_e64 v131, v206, v207, vcc
	v_cndmask_b32_e64 v132, v208, v209, vcc
	v_cndmask_b32_e64 v133, v210, v211, vcc
	v_cndmask_b32_e64 v134, v212, v213, vcc
	ds_bpermute_b32 v200, v68, v119
	ds_bpermute_b32 v201, v68, v115
	ds_bpermute_b32 v202, v68, v108
	ds_bpermute_b32 v203, v68, v104
	ds_bpermute_b32 v204, v68, v109
	ds_bpermute_b32 v205, v68, v105
	ds_bpermute_b32 v206, v68, v110
	ds_bpermute_b32 v207, v68, v106
	ds_bpermute_b32 v208, v68, v111
	ds_bpermute_b32 v209, v68, v107
	ds_bpermute_b32 v210, v68, v100
	ds_bpermute_b32 v211, v68, v96
	ds_bpermute_b32 v212, v68, v101
	ds_bpermute_b32 v213, v68, v97
	s_waitcnt lgkmcnt(0)
	v_cndmask_b32_e64 v135, v200, v201, vcc
	v_cndmask_b32_e64 v136, v202, v203, vcc
	v_cndmask_b32_e64 v137, v204, v205, vcc
	v_cndmask_b32_e64 v138, v206, v207, vcc
	v_cndmask_b32_e64 v139, v208, v209, vcc
	v_cndmask_b32_e64 v140, v210, v211, vcc
	v_cndmask_b32_e64 v141, v212, v213, vcc
	ds_bpermute_b32 v200, v68, v102
	ds_bpermute_b32 v201, v68, v98
	ds_bpermute_b32 v202, v68, v103
	ds_bpermute_b32 v203, v68, v99
	ds_bpermute_b32 v204, v69, v124
	ds_bpermute_b32 v205, v69, v120
	ds_bpermute_b32 v206, v69, v125
	ds_bpermute_b32 v207, v69, v121
	ds_bpermute_b32 v208, v69, v126
	ds_bpermute_b32 v209, v69, v122
	ds_bpermute_b32 v210, v69, v127
	ds_bpermute_b32 v211, v69, v123
	ds_bpermute_b32 v212, v69, v116
	ds_bpermute_b32 v213, v69, v112
	s_waitcnt lgkmcnt(0)
	v_cndmask_b32_e64 v142, v200, v201, vcc
	v_cndmask_b32_e64 v143, v202, v203, vcc
	v_cndmask_b32_e64 v144, v204, v205, vcc
	v_cndmask_b32_e64 v145, v206, v207, vcc
	v_cndmask_b32_e64 v146, v208, v209, vcc
	v_cndmask_b32_e64 v147, v210, v211, vcc
	v_cndmask_b32_e64 v148, v212, v213, vcc
	ds_bpermute_b32 v200, v69, v117
	ds_bpermute_b32 v201, v69, v113
	ds_bpermute_b32 v202, v69, v118
	ds_bpermute_b32 v203, v69, v114
	ds_bpermute_b32 v204, v69, v119
	ds_bpermute_b32 v205, v69, v115
	ds_bpermute_b32 v206, v69, v108
	ds_bpermute_b32 v207, v69, v104
	ds_bpermute_b32 v208, v69, v109
	ds_bpermute_b32 v209, v69, v105
	ds_bpermute_b32 v210, v69, v110
	ds_bpermute_b32 v211, v69, v106
	ds_bpermute_b32 v212, v69, v111
	ds_bpermute_b32 v213, v69, v107
	s_waitcnt lgkmcnt(0)
; __device__ __forceinline__ void qkt(f32x16& p0, f32x16& p1, const bf16* Ks, const bf16x8* qr, int r32, int hi) {
;   p0 = f32x16{}; p1 = f32x16{};
; #pragma unroll
;   for (int d0 = 0; d0 < 8; ++d0) { int cb = (d0 * 16 + hi * 8) * 2;
;     bf16x8 b0 = *reinterpret_cast<const bf16x8*>((const char*)Ks + KSWZ(r32, cb));
;     bf16x8 b1 = *reinterpret_cast<const bf16x8*>((const char*)Ks + KSWZ(32 + r32, cb));
;     p0 = __builtin_amdgcn_mfma_f32_32x32x16_bf16(b0, qr[d0], p0, 0, 0, 0);
;     p1 = __builtin_amdgcn_mfma_f32_32x32x16_bf16(b1, qr[d0], p1, 0, 0, 0); }
; }
;     ...
;   PLOAD(0); asm volatile("s_waitcnt vmcnt(0)" ::: "memory"); PWRITE(0); __syncthreads();
;   qkt(pA0, pA1, KSUB(0, 0), qr, r32, hi); partialSM(pA0, pA1, m_reg, mnA, alA);
	v_cndmask_b32_e64 v149, v200, v201, vcc
	v_cndmask_b32_e64 v150, v202, v203, vcc
	v_cndmask_b32_e64 v151, v204, v205, vcc
	v_cndmask_b32_e64 v152, v206, v207, vcc
	v_cndmask_b32_e64 v153, v208, v209, vcc
	v_cndmask_b32_e64 v154, v210, v211, vcc
	v_cndmask_b32_e64 v155, v212, v213, vcc
	ds_bpermute_b32 v200, v69, v100
	ds_bpermute_b32 v201, v69, v96
	ds_bpermute_b32 v202, v69, v101
	ds_bpermute_b32 v203, v69, v97
	ds_bpermute_b32 v204, v69, v102
	ds_bpermute_b32 v205, v69, v98
	ds_bpermute_b32 v206, v69, v103
	ds_bpermute_b32 v207, v69, v99
	s_waitcnt lgkmcnt(0)
	v_cndmask_b32_e64 v156, v200, v201, vcc
	v_cndmask_b32_e64 v157, v202, v203, vcc
	v_cndmask_b32_e64 v158, v204, v205, vcc
	v_cndmask_b32_e64 v159, v206, v207, vcc
	v_mov_b32_e32 v96, v128
	v_mov_b32_e32 v97, v129
	v_mov_b32_e32 v98, v130
	v_mov_b32_e32 v99, v131
	v_mov_b32_e32 v100, v132
	v_mov_b32_e32 v101, v133
	v_mov_b32_e32 v102, v134
	v_mov_b32_e32 v103, v135
	v_mov_b32_e32 v104, v136
	v_mov_b32_e32 v105, v137
	v_mov_b32_e32 v106, v138
	v_mov_b32_e32 v107, v139
	v_mov_b32_e32 v108, v140
	v_mov_b32_e32 v109, v141
	v_mov_b32_e32 v110, v142
	v_mov_b32_e32 v111, v143
	v_mov_b32_e32 v112, v144
	v_mov_b32_e32 v113, v145
	v_mov_b32_e32 v114, v146
	v_mov_b32_e32 v115, v147
	v_mov_b32_e32 v116, v148
	v_mov_b32_e32 v117, v149
	v_mov_b32_e32 v118, v150
	v_mov_b32_e32 v119, v151
	v_mov_b32_e32 v120, v152
	v_mov_b32_e32 v121, v153
	v_mov_b32_e32 v122, v154
	v_mov_b32_e32 v123, v155
	v_mov_b32_e32 v124, v156
	v_mov_b32_e32 v125, v157
	v_mov_b32_e32 v126, v158
	v_mov_b32_e32 v127, v159
	v_mov_b32_e32 v169, 0
	v_mov_b32_e32 v222, 0
	s_mov_b32 s44, 0
	ds_read_b128 v[200:203], v172 offset:0
	ds_read_b128 v[204:207], v172 offset:4096
	ds_read_b128 v[208:211], v172 offset:8192
	ds_read_b128 v[212:215], v172 offset:12288
	ds_read_b128 v[230:233], v173 offset:0
	ds_read_b128 v[234:237], v173 offset:4096
	ds_read_b128 v[238:241], v173 offset:8192
	ds_read_b128 v[242:245], v173 offset:12288
	s_waitcnt lgkmcnt(6)
	v_mfma_f32_16x16x32_bf16 v[64:67], v[200:203], v[96:99], 0
	v_mfma_f32_16x16x32_bf16 v[68:71], v[200:203], v[112:115], 0
	ds_read_b128 v[200:203], v174 offset:0
	v_mfma_f32_16x16x32_bf16 v[72:75], v[204:207], v[96:99], 0
	v_mfma_f32_16x16x32_bf16 v[76:79], v[204:207], v[112:115], 0
	ds_read_b128 v[204:207], v174 offset:4096
	s_waitcnt lgkmcnt(6)
	v_mfma_f32_16x16x32_bf16 v[80:83], v[208:211], v[96:99], 0
	v_mfma_f32_16x16x32_bf16 v[84:87], v[208:211], v[112:115], 0
	ds_read_b128 v[208:211], v174 offset:8192
	v_mfma_f32_16x16x32_bf16 v[88:91], v[212:215], v[96:99], 0
	v_mfma_f32_16x16x32_bf16 v[92:95], v[212:215], v[112:115], 0
	ds_read_b128 v[212:215], v174 offset:12288
	s_waitcnt lgkmcnt(6)
	v_mfma_f32_16x16x32_bf16 v[64:67], v[230:233], v[100:103], v[64:67]
	v_mfma_f32_16x16x32_bf16 v[68:71], v[230:233], v[116:119], v[68:71]
	ds_read_b128 v[230:233], v175 offset:0
	v_mfma_f32_16x16x32_bf16 v[72:75], v[234:237], v[100:103], v[72:75]
	v_mfma_f32_16x16x32_bf16 v[76:79], v[234:237], v[116:119], v[76:79]
	ds_read_b128 v[234:237], v175 offset:4096
	s_waitcnt lgkmcnt(6)
	v_mfma_f32_16x16x32_bf16 v[80:83], v[238:241], v[100:103], v[80:83]
	v_mfma_f32_16x16x32_bf16 v[84:87], v[238:241], v[116:119], v[84:87]
	ds_read_b128 v[238:241], v175 offset:8192
	v_mfma_f32_16x16x32_bf16 v[88:91], v[242:245], v[100:103], v[88:91]
	v_mfma_f32_16x16x32_bf16 v[92:95], v[242:245], v[116:119], v[92:95]
	ds_read_b128 v[242:245], v175 offset:12288
	s_waitcnt lgkmcnt(6)
	v_mfma_f32_16x16x32_bf16 v[64:67], v[200:203], v[104:107], v[64:67]
	v_mfma_f32_16x16x32_bf16 v[68:71], v[200:203], v[120:123], v[68:71]
	v_mfma_f32_16x16x32_bf16 v[72:75], v[204:207], v[104:107], v[72:75]
	v_mfma_f32_16x16x32_bf16 v[76:79], v[204:207], v[120:123], v[76:79]
	s_waitcnt lgkmcnt(4)
	v_mfma_f32_16x16x32_bf16 v[80:83], v[208:211], v[104:107], v[80:83]
	v_mfma_f32_16x16x32_bf16 v[84:87], v[208:211], v[120:123], v[84:87]
	v_mfma_f32_16x16x32_bf16 v[88:91], v[212:215], v[104:107], v[88:91]
	v_mfma_f32_16x16x32_bf16 v[92:95], v[212:215], v[120:123], v[92:95]
	s_waitcnt lgkmcnt(2)
	v_mfma_f32_16x16x32_bf16 v[64:67], v[230:233], v[108:111], v[64:67]
	v_mfma_f32_16x16x32_bf16 v[68:71], v[230:233], v[124:127], v[68:71]
	v_mfma_f32_16x16x32_bf16 v[72:75], v[234:237], v[108:111], v[72:75]
	v_mfma_f32_16x16x32_bf16 v[76:79], v[234:237], v[124:127], v[76:79]
	s_waitcnt lgkmcnt(0)
	v_mfma_f32_16x16x32_bf16 v[80:83], v[238:241], v[108:111], v[80:83]
	v_mfma_f32_16x16x32_bf16 v[84:87], v[238:241], v[124:127], v[84:87]
	v_mfma_f32_16x16x32_bf16 v[88:91], v[242:245], v[108:111], v[88:91]
	v_mfma_f32_16x16x32_bf16 v[92:95], v[242:245], v[124:127], v[92:95]
	v_exp_f32_e32 v64, v64
	v_exp_f32_e32 v65, v65
	v_exp_f32_e32 v66, v66
	v_exp_f32_e32 v67, v67
	v_exp_f32_e32 v68, v68
	v_exp_f32_e32 v69, v69
	v_exp_f32_e32 v70, v70
	v_exp_f32_e32 v71, v71
	v_exp_f32_e32 v72, v72
	v_exp_f32_e32 v73, v73
	v_exp_f32_e32 v74, v74
	v_exp_f32_e32 v75, v75
	v_exp_f32_e32 v76, v76
	v_exp_f32_e32 v77, v77
	v_exp_f32_e32 v78, v78
	v_exp_f32_e32 v79, v79
	v_exp_f32_e32 v80, v80
	v_exp_f32_e32 v81, v81
	v_exp_f32_e32 v82, v82
	v_exp_f32_e32 v83, v83
	v_exp_f32_e32 v84, v84
	v_exp_f32_e32 v85, v85
	v_exp_f32_e32 v86, v86
	v_exp_f32_e32 v87, v87
	v_exp_f32_e32 v88, v88
	v_exp_f32_e32 v89, v89
	v_exp_f32_e32 v90, v90
	v_exp_f32_e32 v91, v91
	v_exp_f32_e32 v92, v92
	v_exp_f32_e32 v93, v93
	v_exp_f32_e32 v94, v94
	v_exp_f32_e32 v95, v95
	s_waitcnt vmcnt(0)
	ds_read_b128 v[200:203], v172 offset:16384
	ds_read_b128 v[204:207], v172 offset:20480
	ds_read_b128 v[208:211], v172 offset:24576
	ds_read_b128 v[212:215], v172 offset:28672
	ds_read_b128 v[230:233], v173 offset:16384
	ds_read_b128 v[234:237], v173 offset:20480
	ds_read_b128 v[238:241], v173 offset:24576
	ds_read_b128 v[242:245], v173 offset:28672
	s_barrier
	v_readfirstlane_b32 s44, v218
	s_nop 3
	s_cmp_ge_u32 s44, 0x100
	s_mov_b32 s44, 0
	s_cbranch_scc0 .Lprio_done
	s_setprio 1
; __device__ __forceinline__ void finishSM(f32x16& p0, f32x16& p1, float alpha, float& l_reg, bf16x8& pa0, bf16x8& pa1, bf16x8& pa2, bf16x8& pa3) {
; #pragma unroll
;   for (int r = 0; r < 16; ++r) p1[r] = __builtin_amdgcn_exp2f(p1[r]);
;   float ps = 0;
; #pragma unroll
;   for (int r = 0; r < 16; ++r) ps += p0[r];
; #pragma unroll
;   for (int r = 0; r < 16; ++r) ps += p1[r];
;   { auto rr = __builtin_amdgcn_permlane32_swap(__float_as_uint(ps), __float_as_uint(ps), false, false);
;     ps = __uint_as_float(rr[0]) + __uint_as_float(rr[1]); }
;   l_reg = l_reg * alpha + ps;
;     ...
;   PK4(p0, 0, pa0); PK4(p0, 8, pa1); PK4(p1, 0, pa2); PK4(p1, 8, pa3);
;     ...
; }
; __device__ __forceinline__ void qkt(f32x16& p0, f32x16& p1, const bf16* Ks, const bf16x8* qr, int r32, int hi) {
;   p0 = f32x16{}; p1 = f32x16{};
; #pragma unroll
;   for (int d0 = 0; d0 < 8; ++d0) { int cb = (d0 * 16 + hi * 8) * 2;
;     bf16x8 b0 = *reinterpret_cast<const bf16x8*>((const char*)Ks + KSWZ(r32, cb));
;     bf16x8 b1 = *reinterpret_cast<const bf16x8*>((const char*)Ks + KSWZ(32 + r32, cb));
;     p0 = __builtin_amdgcn_mfma_f32_32x32x16_bf16(b0, qr[d0], p0, 0, 0, 0);
;     p1 = __builtin_amdgcn_mfma_f32_32x32x16_bf16(b1, qr[d0], p1, 0, 0, 0); }
; }
; __device__ __forceinline__ int v_st(int k, int c) { const int kk = (k & ~0xC) | ((k & 4) << 1) | ((k & 8) >> 1); return ((kk >> 3) * 4 + (c >> 5)) * 512 + ((kk & 7) * 32 + (c & 31)) * 2; }
; __device__ __forceinline__ int v_rd_base(int lane) { return ((lane & 3) << 3) | (((lane >> 2) & 3) << 6) | (((lane >> 4) & 1) << 5) | (((lane >> 5) & 1) << 8); }
; template <int OFF> __device__ __forceinline__ s16x4 tr_read(int vb) {
;   s16x4 r; asm volatile("ds_read_b64_tr_b16 %0, %1 offset:%2" : "=&v"(r) : "v"(vb), "i"(OFF) : "memory"); return r;
; }
; template <int D0> __device__ __forceinline__ void pv_one(f32x16& od, int vb, bf16x8 pa0, bf16x8 pa1, bf16x8 pa2, bf16x8 pa3) {
;   const s16x4 l0 = tr_read<v_rd_off(D0, 0, 0)>(vb), h0 = tr_read<v_rd_off(D0, 0, 1)>(vb), l1 = tr_read<v_rd_off(D0, 1, 0)>(vb), h1 = tr_read<v_rd_off(D0, 1, 1)>(vb);
;   const s16x4 l2 = tr_read<v_rd_off(D0, 2, 0)>(vb), h2 = tr_read<v_rd_off(D0, 2, 1)>(vb), l3 = tr_read<v_rd_off(D0, 3, 0)>(vb), h3 = tr_read<v_rd_off(D0, 3, 1)>(vb);
;   asm volatile("s_waitcnt lgkmcnt(0)" ::: "memory"); SBAR();
;     ...
;   od = __builtin_amdgcn_mfma_f32_32x32x16_bf16(pa0, PK(l0, h0), od, 0, 0, 0);
.Lprio_done:
.Ldense_loop:
	s_waitcnt lgkmcnt(6)
	v_mfma_f32_16x16x32_bf16 v[128:131], v[200:203], v[96:99], 0
	v_add_f32_e32 v169, v169, v64
	s_add_i32 m0, s32, 0x0
	v_mfma_f32_16x16x32_bf16 v[132:135], v[200:203], v[112:115], 0
	ds_read_b128 v[200:203], v174 offset:16384
	v_add_f32_e32 v169, v169, v65
	v_cvt_pk_bf16_f32 v184, v64, v65
	global_load_lds_dwordx4 v183, s[98:99]
	v_mfma_f32_16x16x32_bf16 v[136:139], v[204:207], v[96:99], 0
	v_add_f32_e32 v169, v169, v66
	v_mfma_f32_16x16x32_bf16 v[140:143], v[204:207], v[112:115], 0
	ds_read_b128 v[204:207], v174 offset:20480
	v_add_f32_e32 v169, v169, v67
	v_cvt_pk_bf16_f32 v185, v66, v67
	s_waitcnt lgkmcnt(6)
	v_mfma_f32_16x16x32_bf16 v[144:147], v[208:211], v[96:99], 0
	v_add_f32_e32 v222, v222, v68
	s_add_i32 m0, s32, 0x2000
	v_mfma_f32_16x16x32_bf16 v[148:151], v[208:211], v[112:115], 0
	ds_read_b128 v[208:211], v174 offset:24576
	v_add_f32_e32 v222, v222, v69
	v_cvt_pk_bf16_f32 v186, v72, v73
	global_load_lds_dwordx4 v246, s[98:99]
	s_add_u32 s98, s98, 0x150000
	s_addc_u32 s99, s99, 0
	v_mfma_f32_16x16x32_bf16 v[152:155], v[212:215], v[96:99], 0
	v_add_f32_e32 v222, v222, v70
	v_mfma_f32_16x16x32_bf16 v[156:159], v[212:215], v[112:115], 0
	ds_read_b128 v[212:215], v174 offset:28672
	v_add_f32_e32 v222, v222, v71
	v_cvt_pk_bf16_f32 v187, v74, v75
	s_waitcnt lgkmcnt(6)
	v_mfma_f32_16x16x32_bf16 v[128:131], v[230:233], v[100:103], v[128:131]
	v_add_f32_e32 v169, v169, v72
	s_add_i32 m0, s32, 0x18000
	v_mfma_f32_16x16x32_bf16 v[132:135], v[230:233], v[116:119], v[132:135]
	ds_read_b128 v[230:233], v175 offset:16384
	v_add_f32_e32 v169, v169, v73
	v_cvt_pk_bf16_f32 v188, v80, v81
	global_load_lds_dwordx4 v181, s[0:1]
	v_mfma_f32_16x16x32_bf16 v[136:139], v[234:237], v[100:103], v[136:139]
	v_add_f32_e32 v169, v169, v74
	v_mfma_f32_16x16x32_bf16 v[140:143], v[234:237], v[116:119], v[140:143]
	ds_read_b128 v[234:237], v175 offset:20480
	v_add_f32_e32 v169, v169, v75
	v_cvt_pk_bf16_f32 v189, v82, v83
	s_waitcnt lgkmcnt(6)
	v_mfma_f32_16x16x32_bf16 v[144:147], v[238:241], v[100:103], v[144:147]
	v_add_f32_e32 v222, v222, v76
	s_add_i32 m0, s32, 0x1a000
	v_mfma_f32_16x16x32_bf16 v[148:151], v[238:241], v[116:119], v[148:151]
	ds_read_b128 v[238:241], v175 offset:24576
	v_add_f32_e32 v222, v222, v77
	v_cvt_pk_bf16_f32 v190, v88, v89
	global_load_lds_dwordx4 v247, s[0:1]
	s_add_u32 s0, s0, 0x150000
	s_addc_u32 s1, s1, 0
	v_mfma_f32_16x16x32_bf16 v[152:155], v[242:245], v[100:103], v[152:155]
	v_add_f32_e32 v222, v222, v78
	v_mfma_f32_16x16x32_bf16 v[156:159], v[242:245], v[116:119], v[156:159]
	ds_read_b128 v[242:245], v175 offset:28672
	v_add_f32_e32 v222, v222, v79
	v_cvt_pk_bf16_f32 v191, v90, v91
	s_waitcnt lgkmcnt(6)
	v_mfma_f32_16x16x32_bf16 v[128:131], v[200:203], v[104:107], v[128:131]
	v_add_f32_e32 v169, v169, v80
	v_mfma_f32_16x16x32_bf16 v[132:135], v[200:203], v[120:123], v[132:135]
	v_add_f32_e32 v169, v169, v81
	v_cvt_pk_bf16_f32 v192, v68, v69
	v_mfma_f32_16x16x32_bf16 v[136:139], v[204:207], v[104:107], v[136:139]
	v_add_f32_e32 v169, v169, v82
	v_mfma_f32_16x16x32_bf16 v[140:143], v[204:207], v[120:123], v[140:143]
	v_add_f32_e32 v169, v169, v83
	v_cvt_pk_bf16_f32 v193, v70, v71
	s_waitcnt lgkmcnt(4)
	v_mfma_f32_16x16x32_bf16 v[144:147], v[208:211], v[104:107], v[144:147]
	ds_read_b64_tr_b16 v[200:201], v176 offset:0
	ds_read_b64_tr_b16 v[202:203], v176 offset:4096
	v_add_f32_e32 v222, v222, v84
	v_mfma_f32_16x16x32_bf16 v[148:151], v[208:211], v[120:123], v[148:151]
	v_add_f32_e32 v222, v222, v85
	v_cvt_pk_bf16_f32 v194, v76, v77
	v_mfma_f32_16x16x32_bf16 v[152:155], v[212:215], v[104:107], v[152:155]
	ds_read_b64_tr_b16 v[204:205], v177 offset:0
	ds_read_b64_tr_b16 v[206:207], v177 offset:4096
	v_add_f32_e32 v222, v222, v86
	v_mfma_f32_16x16x32_bf16 v[156:159], v[212:215], v[120:123], v[156:159]
	v_add_f32_e32 v222, v222, v87
	v_cvt_pk_bf16_f32 v195, v78, v79
	s_waitcnt lgkmcnt(6)
	v_mfma_f32_16x16x32_bf16 v[128:131], v[230:233], v[108:111], v[128:131]
	ds_read_b64_tr_b16 v[208:209], v178 offset:0
	ds_read_b64_tr_b16 v[210:211], v178 offset:4096
	v_add_f32_e32 v169, v169, v88
	v_mfma_f32_16x16x32_bf16 v[132:135], v[230:233], v[124:127], v[132:135]
	v_add_f32_e32 v169, v169, v89
	v_cvt_pk_bf16_f32 v196, v84, v85
	v_mfma_f32_16x16x32_bf16 v[136:139], v[234:237], v[108:111], v[136:139]
	ds_read_b64_tr_b16 v[212:213], v179 offset:0
	ds_read_b64_tr_b16 v[214:215], v179 offset:4096
	v_add_f32_e32 v169, v169, v90
	v_mfma_f32_16x16x32_bf16 v[140:143], v[234:237], v[124:127], v[140:143]
	v_add_f32_e32 v169, v169, v91
	v_cvt_pk_bf16_f32 v197, v86, v87
	s_waitcnt lgkmcnt(8)
	v_mfma_f32_16x16x32_bf16 v[144:147], v[238:241], v[108:111], v[144:147]
	ds_read_b64_tr_b16 v[230:231], v180 offset:0
	ds_read_b64_tr_b16 v[232:233], v180 offset:4096
	v_add_f32_e32 v222, v222, v92
	v_mfma_f32_16x16x32_bf16 v[148:151], v[238:241], v[124:127], v[148:151]
	v_add_f32_e32 v222, v222, v93
	v_cvt_pk_bf16_f32 v198, v92, v93
	v_mfma_f32_16x16x32_bf16 v[152:155], v[242:245], v[108:111], v[152:155]
	ds_read_b64_tr_b16 v[234:235], v182 offset:0
	ds_read_b64_tr_b16 v[236:237], v182 offset:4096
	v_add_f32_e32 v222, v222, v94
	v_mfma_f32_16x16x32_bf16 v[156:159], v[242:245], v[124:127], v[156:159]
	v_add_f32_e32 v222, v222, v95
	v_cvt_pk_bf16_f32 v199, v94, v95
	s_waitcnt lgkmcnt(8)
	v_mfma_f32_16x16x32_bf16 v[0:3], v[200:203], v[184:187], v[0:3]
	v_exp_f32_e32 v128, v128
	v_mfma_f32_16x16x32_bf16 v[32:35], v[200:203], v[192:195], v[32:35]
	ds_read_b64_tr_b16 v[238:239], v216 offset:0
	ds_read_b64_tr_b16 v[240:241], v216 offset:4096
	v_exp_f32_e32 v129, v129
	v_mfma_f32_16x16x32_bf16 v[4:7], v[204:207], v[184:187], v[4:7]
	v_exp_f32_e32 v130, v130
	v_mfma_f32_16x16x32_bf16 v[36:39], v[204:207], v[192:195], v[36:39]
	ds_read_b64_tr_b16 v[242:243], v217 offset:0
	ds_read_b64_tr_b16 v[244:245], v217 offset:4096
	v_exp_f32_e32 v131, v131
	s_waitcnt lgkmcnt(8)
; __device__ __forceinline__ void partialSM(f32x16& p0, f32x16& p1, float& m_reg, float& mn, float& alpha) {
;     ...
;   for (int r = 0; r < 16; ++r) p0[r] = __builtin_amdgcn_exp2f(p0[r]);
; }
; __device__ __forceinline__ void finishSM(f32x16& p0, f32x16& p1, float alpha, float& l_reg, bf16x8& pa0, bf16x8& pa1, bf16x8& pa2, bf16x8& pa3) {
; #pragma unroll
;   for (int r = 0; r < 16; ++r) p1[r] = __builtin_amdgcn_exp2f(p1[r]);
;   float ps = 0;
; #pragma unroll
;   for (int r = 0; r < 16; ++r) ps += p0[r];
; #pragma unroll
;   for (int r = 0; r < 16; ++r) ps += p1[r];
;   { auto rr = __builtin_amdgcn_permlane32_swap(__float_as_uint(ps), __float_as_uint(ps), false, false);
;     ps = __uint_as_float(rr[0]) + __uint_as_float(rr[1]); }
;   l_reg = l_reg * alpha + ps;
;     ...
;   PK4(p0, 0, pa0); PK4(p0, 8, pa1); PK4(p1, 0, pa2); PK4(p1, 8, pa3);
;     ...
; }
; __device__ __forceinline__ void qkt(f32x16& p0, f32x16& p1, const bf16* Ks, const bf16x8* qr, int r32, int hi) {
;   p0 = f32x16{}; p1 = f32x16{};
; #pragma unroll
;   for (int d0 = 0; d0 < 8; ++d0) { int cb = (d0 * 16 + hi * 8) * 2;
;     bf16x8 b0 = *reinterpret_cast<const bf16x8*>((const char*)Ks + KSWZ(r32, cb));
;     bf16x8 b1 = *reinterpret_cast<const bf16x8*>((const char*)Ks + KSWZ(32 + r32, cb));
;     p0 = __builtin_amdgcn_mfma_f32_32x32x16_bf16(b0, qr[d0], p0, 0, 0, 0);
;     p1 = __builtin_amdgcn_mfma_f32_32x32x16_bf16(b1, qr[d0], p1, 0, 0, 0); }
; }
; __device__ __forceinline__ int v_st(int k, int c) { const int kk = (k & ~0xC) | ((k & 4) << 1) | ((k & 8) >> 1); return ((kk >> 3) * 4 + (c >> 5)) * 512 + ((kk & 7) * 32 + (c & 31)) * 2; }
; __device__ __forceinline__ int v_rd_base(int lane) { return ((lane & 3) << 3) | (((lane >> 2) & 3) << 6) | (((lane >> 4) & 1) << 5) | (((lane >> 5) & 1) << 8); }
; template <int OFF> __device__ __forceinline__ s16x4 tr_read(int vb) {
;   s16x4 r; asm volatile("ds_read_b64_tr_b16 %0, %1 offset:%2" : "=&v"(r) : "v"(vb), "i"(OFF) : "memory"); return r;
; }
; template <int D0> __device__ __forceinline__ void pv_one(f32x16& od, int vb, bf16x8 pa0, bf16x8 pa1, bf16x8 pa2, bf16x8 pa3) {
;   const s16x4 l0 = tr_read<v_rd_off(D0, 0, 0)>(vb), h0 = tr_read<v_rd_off(D0, 0, 1)>(vb), l1 = tr_read<v_rd_off(D0, 1, 0)>(vb), h1 = tr_read<v_rd_off(D0, 1, 1)>(vb);
	v_mfma_f32_16x16x32_bf16 v[8:11], v[208:211], v[184:187], v[8:11]
	v_exp_f32_e32 v132, v132
	v_mfma_f32_16x16x32_bf16 v[40:43], v[208:211], v[192:195], v[40:43]
	ds_read_b64_tr_b16 v[200:201], v176 offset:8192
	ds_read_b64_tr_b16 v[202:203], v176 offset:12288
	v_exp_f32_e32 v133, v133
	v_mfma_f32_16x16x32_bf16 v[12:15], v[212:215], v[184:187], v[12:15]
	v_exp_f32_e32 v134, v134
	v_mfma_f32_16x16x32_bf16 v[44:47], v[212:215], v[192:195], v[44:47]
	ds_read_b64_tr_b16 v[204:205], v177 offset:8192
	ds_read_b64_tr_b16 v[206:207], v177 offset:12288
	v_exp_f32_e32 v135, v135
	s_waitcnt lgkmcnt(8)
	v_mfma_f32_16x16x32_bf16 v[16:19], v[230:233], v[184:187], v[16:19]
	v_exp_f32_e32 v136, v136
	v_mfma_f32_16x16x32_bf16 v[48:51], v[230:233], v[192:195], v[48:51]
	ds_read_b64_tr_b16 v[208:209], v178 offset:8192
	ds_read_b64_tr_b16 v[210:211], v178 offset:12288
	v_exp_f32_e32 v137, v137
	v_mfma_f32_16x16x32_bf16 v[20:23], v[234:237], v[184:187], v[20:23]
	v_exp_f32_e32 v138, v138
	v_mfma_f32_16x16x32_bf16 v[52:55], v[234:237], v[192:195], v[52:55]
	ds_read_b64_tr_b16 v[212:213], v179 offset:8192
	ds_read_b64_tr_b16 v[214:215], v179 offset:12288
	v_exp_f32_e32 v139, v139
	s_waitcnt lgkmcnt(8)
	v_mfma_f32_16x16x32_bf16 v[24:27], v[238:241], v[184:187], v[24:27]
	v_exp_f32_e32 v140, v140
	v_mfma_f32_16x16x32_bf16 v[56:59], v[238:241], v[192:195], v[56:59]
	ds_read_b64_tr_b16 v[230:231], v180 offset:8192
	ds_read_b64_tr_b16 v[232:233], v180 offset:12288
	v_exp_f32_e32 v141, v141
	v_mfma_f32_16x16x32_bf16 v[28:31], v[242:245], v[184:187], v[28:31]
	v_exp_f32_e32 v142, v142
	v_mfma_f32_16x16x32_bf16 v[60:63], v[242:245], v[192:195], v[60:63]
	ds_read_b64_tr_b16 v[234:235], v182 offset:8192
	ds_read_b64_tr_b16 v[236:237], v182 offset:12288
	v_exp_f32_e32 v143, v143
	s_waitcnt lgkmcnt(8)
	v_mfma_f32_16x16x32_bf16 v[0:3], v[200:203], v[188:191], v[0:3]
	v_exp_f32_e32 v144, v144
	v_mfma_f32_16x16x32_bf16 v[32:35], v[200:203], v[196:199], v[32:35]
	ds_read_b64_tr_b16 v[238:239], v216 offset:8192
	ds_read_b64_tr_b16 v[240:241], v216 offset:12288
	ds_read_b128 v[200:203], v172 offset:32768
	v_exp_f32_e32 v145, v145
	v_mfma_f32_16x16x32_bf16 v[4:7], v[204:207], v[188:191], v[4:7]
	v_exp_f32_e32 v146, v146
	v_mfma_f32_16x16x32_bf16 v[36:39], v[204:207], v[196:199], v[36:39]
	ds_read_b64_tr_b16 v[242:243], v217 offset:8192
	ds_read_b64_tr_b16 v[244:245], v217 offset:12288
	ds_read_b128 v[204:207], v172 offset:36864
	v_exp_f32_e32 v147, v147
	s_waitcnt lgkmcnt(10)
	v_mfma_f32_16x16x32_bf16 v[8:11], v[208:211], v[188:191], v[8:11]
	v_exp_f32_e32 v148, v148
	v_mfma_f32_16x16x32_bf16 v[40:43], v[208:211], v[196:199], v[40:43]
	ds_read_b128 v[208:211], v172 offset:40960
	v_exp_f32_e32 v149, v149
	v_mfma_f32_16x16x32_bf16 v[12:15], v[212:215], v[188:191], v[12:15]
	v_exp_f32_e32 v150, v150
	v_mfma_f32_16x16x32_bf16 v[44:47], v[212:215], v[196:199], v[44:47]
	ds_read_b128 v[212:215], v172 offset:45056
	v_exp_f32_e32 v151, v151
	s_waitcnt lgkmcnt(8)
	v_mfma_f32_16x16x32_bf16 v[16:19], v[230:233], v[188:191], v[16:19]
	v_exp_f32_e32 v152, v152
	v_mfma_f32_16x16x32_bf16 v[48:51], v[230:233], v[196:199], v[48:51]
	ds_read_b128 v[230:233], v173 offset:32768
	v_exp_f32_e32 v153, v153
	v_mfma_f32_16x16x32_bf16 v[20:23], v[234:237], v[188:191], v[20:23]
	v_exp_f32_e32 v154, v154
	v_mfma_f32_16x16x32_bf16 v[52:55], v[234:237], v[196:199], v[52:55]
	ds_read_b128 v[234:237], v173 offset:36864
	v_exp_f32_e32 v155, v155
	s_waitcnt lgkmcnt(5)
	v_mfma_f32_16x16x32_bf16 v[24:27], v[238:241], v[188:191], v[24:27]
	v_exp_f32_e32 v156, v156
	v_mfma_f32_16x16x32_bf16 v[56:59], v[238:241], v[196:199], v[56:59]
	ds_read_b128 v[238:241], v173 offset:40960
	v_exp_f32_e32 v157, v157
	v_mfma_f32_16x16x32_bf16 v[28:31], v[242:245], v[188:191], v[28:31]
	v_exp_f32_e32 v158, v158
	v_mfma_f32_16x16x32_bf16 v[60:63], v[242:245], v[196:199], v[60:63]
	ds_read_b128 v[242:245], v173 offset:45056
	v_exp_f32_e32 v159, v159
	s_waitcnt vmcnt(4)
	s_barrier
	s_waitcnt lgkmcnt(6)
	v_mfma_f32_16x16x32_bf16 v[64:67], v[200:203], v[96:99], 0
	v_add_f32_e32 v169, v169, v128
	s_add_i32 m0, s32, 0x4000
	v_mfma_f32_16x16x32_bf16 v[68:71], v[200:203], v[112:115], 0
	ds_read_b128 v[200:203], v174 offset:32768
	v_add_f32_e32 v169, v169, v129
	v_cvt_pk_bf16_f32 v184, v128, v129
	global_load_lds_dwordx4 v183, s[98:99]
	v_mfma_f32_16x16x32_bf16 v[72:75], v[204:207], v[96:99], 0
	v_add_f32_e32 v169, v169, v130
	v_mfma_f32_16x16x32_bf16 v[76:79], v[204:207], v[112:115], 0
	ds_read_b128 v[204:207], v174 offset:36864
	v_add_f32_e32 v169, v169, v131
	v_cvt_pk_bf16_f32 v185, v130, v131
	s_waitcnt lgkmcnt(6)
	v_mfma_f32_16x16x32_bf16 v[80:83], v[208:211], v[96:99], 0
	v_add_f32_e32 v222, v222, v132
	s_add_i32 m0, s32, 0x6000
	v_mfma_f32_16x16x32_bf16 v[84:87], v[208:211], v[112:115], 0
	ds_read_b128 v[208:211], v174 offset:40960
	v_add_f32_e32 v222, v222, v133
	v_cvt_pk_bf16_f32 v186, v136, v137
	global_load_lds_dwordx4 v246, s[98:99]
	s_add_u32 s98, s98, 0x150000
	s_addc_u32 s99, s99, 0
	v_mfma_f32_16x16x32_bf16 v[88:91], v[212:215], v[96:99], 0
	v_add_f32_e32 v222, v222, v134
	v_mfma_f32_16x16x32_bf16 v[92:95], v[212:215], v[112:115], 0
	ds_read_b128 v[212:215], v174 offset:45056
	v_add_f32_e32 v222, v222, v135
	v_cvt_pk_bf16_f32 v187, v138, v139
	s_waitcnt lgkmcnt(6)
	v_mfma_f32_16x16x32_bf16 v[64:67], v[230:233], v[100:103], v[64:67]
	v_add_f32_e32 v169, v169, v136
	s_add_i32 m0, s32, 0x1c000
	v_mfma_f32_16x16x32_bf16 v[68:71], v[230:233], v[116:119], v[68:71]
	ds_read_b128 v[230:233], v175 offset:32768
	v_add_f32_e32 v169, v169, v137
	v_cvt_pk_bf16_f32 v188, v144, v145
	global_load_lds_dwordx4 v181, s[0:1]
	v_mfma_f32_16x16x32_bf16 v[72:75], v[234:237], v[100:103], v[72:75]
	v_add_f32_e32 v169, v169, v138
	v_mfma_f32_16x16x32_bf16 v[76:79], v[234:237], v[116:119], v[76:79]
	ds_read_b128 v[234:237], v175 offset:36864
	v_add_f32_e32 v169, v169, v139
	v_cvt_pk_bf16_f32 v189, v146, v147
	s_waitcnt lgkmcnt(6)
; __device__ __forceinline__ void partialSM(f32x16& p0, f32x16& p1, float& m_reg, float& mn, float& alpha) {
;     ...
;   for (int r = 0; r < 16; ++r) p0[r] = __builtin_amdgcn_exp2f(p0[r]);
; }
; __device__ __forceinline__ void finishSM(f32x16& p0, f32x16& p1, float alpha, float& l_reg, bf16x8& pa0, bf16x8& pa1, bf16x8& pa2, bf16x8& pa3) {
; #pragma unroll
;   for (int r = 0; r < 16; ++r) p1[r] = __builtin_amdgcn_exp2f(p1[r]);
;   float ps = 0;
; #pragma unroll
;   for (int r = 0; r < 16; ++r) ps += p0[r];
; #pragma unroll
;   for (int r = 0; r < 16; ++r) ps += p1[r];
;   { auto rr = __builtin_amdgcn_permlane32_swap(__float_as_uint(ps), __float_as_uint(ps), false, false);
;     ps = __uint_as_float(rr[0]) + __uint_as_float(rr[1]); }
;   l_reg = l_reg * alpha + ps;
;     ...
;   PK4(p0, 0, pa0); PK4(p0, 8, pa1); PK4(p1, 0, pa2); PK4(p1, 8, pa3);
;     ...
; }
; __device__ __forceinline__ void qkt(f32x16& p0, f32x16& p1, const bf16* Ks, const bf16x8* qr, int r32, int hi) {
;   p0 = f32x16{}; p1 = f32x16{};
; #pragma unroll
;   for (int d0 = 0; d0 < 8; ++d0) { int cb = (d0 * 16 + hi * 8) * 2;
;     bf16x8 b0 = *reinterpret_cast<const bf16x8*>((const char*)Ks + KSWZ(r32, cb));
;     bf16x8 b1 = *reinterpret_cast<const bf16x8*>((const char*)Ks + KSWZ(32 + r32, cb));
;     p0 = __builtin_amdgcn_mfma_f32_32x32x16_bf16(b0, qr[d0], p0, 0, 0, 0);
;     p1 = __builtin_amdgcn_mfma_f32_32x32x16_bf16(b1, qr[d0], p1, 0, 0, 0); }
; }
; __device__ __forceinline__ int v_st(int k, int c) { const int kk = (k & ~0xC) | ((k & 4) << 1) | ((k & 8) >> 1); return ((kk >> 3) * 4 + (c >> 5)) * 512 + ((kk & 7) * 32 + (c & 31)) * 2; }
; __device__ __forceinline__ int v_rd_base(int lane) { return ((lane & 3) << 3) | (((lane >> 2) & 3) << 6) | (((lane >> 4) & 1) << 5) | (((lane >> 5) & 1) << 8); }
; template <int OFF> __device__ __forceinline__ s16x4 tr_read(int vb) {
;   s16x4 r; asm volatile("ds_read_b64_tr_b16 %0, %1 offset:%2" : "=&v"(r) : "v"(vb), "i"(OFF) : "memory"); return r;
; }
; template <int D0> __device__ __forceinline__ void pv_one(f32x16& od, int vb, bf16x8 pa0, bf16x8 pa1, bf16x8 pa2, bf16x8 pa3) {
;   const s16x4 l0 = tr_read<v_rd_off(D0, 0, 0)>(vb), h0 = tr_read<v_rd_off(D0, 0, 1)>(vb), l1 = tr_read<v_rd_off(D0, 1, 0)>(vb), h1 = tr_read<v_rd_off(D0, 1, 1)>(vb);
	v_mfma_f32_16x16x32_bf16 v[80:83], v[238:241], v[100:103], v[80:83]
	v_add_f32_e32 v222, v222, v140
	s_add_i32 m0, s32, 0x1e000
	v_mfma_f32_16x16x32_bf16 v[84:87], v[238:241], v[116:119], v[84:87]
	ds_read_b128 v[238:241], v175 offset:40960
	v_add_f32_e32 v222, v222, v141
	v_cvt_pk_bf16_f32 v190, v152, v153
	global_load_lds_dwordx4 v247, s[0:1]
	s_add_u32 s0, s0, 0x150000
	s_addc_u32 s1, s1, 0
	v_mfma_f32_16x16x32_bf16 v[88:91], v[242:245], v[100:103], v[88:91]
	v_add_f32_e32 v222, v222, v142
	v_mfma_f32_16x16x32_bf16 v[92:95], v[242:245], v[116:119], v[92:95]
	ds_read_b128 v[242:245], v175 offset:45056
	v_add_f32_e32 v222, v222, v143
	v_cvt_pk_bf16_f32 v191, v154, v155
	s_waitcnt lgkmcnt(6)
	v_mfma_f32_16x16x32_bf16 v[64:67], v[200:203], v[104:107], v[64:67]
	v_add_f32_e32 v169, v169, v144
	v_mfma_f32_16x16x32_bf16 v[68:71], v[200:203], v[120:123], v[68:71]
	v_add_f32_e32 v169, v169, v145
	v_cvt_pk_bf16_f32 v192, v132, v133
	v_mfma_f32_16x16x32_bf16 v[72:75], v[204:207], v[104:107], v[72:75]
	v_add_f32_e32 v169, v169, v146
	v_mfma_f32_16x16x32_bf16 v[76:79], v[204:207], v[120:123], v[76:79]
	v_add_f32_e32 v169, v169, v147
	v_cvt_pk_bf16_f32 v193, v134, v135
	s_waitcnt lgkmcnt(4)
	v_mfma_f32_16x16x32_bf16 v[80:83], v[208:211], v[104:107], v[80:83]
	ds_read_b64_tr_b16 v[200:201], v176 offset:16384
	ds_read_b64_tr_b16 v[202:203], v176 offset:20480
	v_add_f32_e32 v222, v222, v148
	v_mfma_f32_16x16x32_bf16 v[84:87], v[208:211], v[120:123], v[84:87]
	v_add_f32_e32 v222, v222, v149
	v_cvt_pk_bf16_f32 v194, v140, v141
	v_mfma_f32_16x16x32_bf16 v[88:91], v[212:215], v[104:107], v[88:91]
	ds_read_b64_tr_b16 v[204:205], v177 offset:16384
	ds_read_b64_tr_b16 v[206:207], v177 offset:20480
	v_add_f32_e32 v222, v222, v150
	v_mfma_f32_16x16x32_bf16 v[92:95], v[212:215], v[120:123], v[92:95]
	v_add_f32_e32 v222, v222, v151
	v_cvt_pk_bf16_f32 v195, v142, v143
	s_waitcnt lgkmcnt(6)
	v_mfma_f32_16x16x32_bf16 v[64:67], v[230:233], v[108:111], v[64:67]
	ds_read_b64_tr_b16 v[208:209], v178 offset:16384
	ds_read_b64_tr_b16 v[210:211], v178 offset:20480
	v_add_f32_e32 v169, v169, v152
	v_mfma_f32_16x16x32_bf16 v[68:71], v[230:233], v[124:127], v[68:71]
	v_add_f32_e32 v169, v169, v153
	v_cvt_pk_bf16_f32 v196, v148, v149
	v_mfma_f32_16x16x32_bf16 v[72:75], v[234:237], v[108:111], v[72:75]
	ds_read_b64_tr_b16 v[212:213], v179 offset:16384
	ds_read_b64_tr_b16 v[214:215], v179 offset:20480
	v_add_f32_e32 v169, v169, v154
	v_mfma_f32_16x16x32_bf16 v[76:79], v[234:237], v[124:127], v[76:79]
	v_add_f32_e32 v169, v169, v155
	v_cvt_pk_bf16_f32 v197, v150, v151
	s_waitcnt lgkmcnt(8)
	v_mfma_f32_16x16x32_bf16 v[80:83], v[238:241], v[108:111], v[80:83]
	ds_read_b64_tr_b16 v[230:231], v180 offset:16384
	ds_read_b64_tr_b16 v[232:233], v180 offset:20480
	v_add_f32_e32 v222, v222, v156
	v_mfma_f32_16x16x32_bf16 v[84:87], v[238:241], v[124:127], v[84:87]
	v_add_f32_e32 v222, v222, v157
	v_cvt_pk_bf16_f32 v198, v156, v157
	v_mfma_f32_16x16x32_bf16 v[88:91], v[242:245], v[108:111], v[88:91]
	ds_read_b64_tr_b16 v[234:235], v182 offset:16384
	ds_read_b64_tr_b16 v[236:237], v182 offset:20480
	v_add_f32_e32 v222, v222, v158
	v_mfma_f32_16x16x32_bf16 v[92:95], v[242:245], v[124:127], v[92:95]
	v_add_f32_e32 v222, v222, v159
	v_cvt_pk_bf16_f32 v199, v158, v159
	s_waitcnt lgkmcnt(8)
	v_mfma_f32_16x16x32_bf16 v[0:3], v[200:203], v[184:187], v[0:3]
	v_exp_f32_e32 v64, v64
	v_mfma_f32_16x16x32_bf16 v[32:35], v[200:203], v[192:195], v[32:35]
	ds_read_b64_tr_b16 v[238:239], v216 offset:16384
	ds_read_b64_tr_b16 v[240:241], v216 offset:20480
	v_exp_f32_e32 v65, v65
	v_mfma_f32_16x16x32_bf16 v[4:7], v[204:207], v[184:187], v[4:7]
	v_exp_f32_e32 v66, v66
	v_mfma_f32_16x16x32_bf16 v[36:39], v[204:207], v[192:195], v[36:39]
	ds_read_b64_tr_b16 v[242:243], v217 offset:16384
	ds_read_b64_tr_b16 v[244:245], v217 offset:20480
	v_exp_f32_e32 v67, v67
	s_waitcnt lgkmcnt(8)
	v_mfma_f32_16x16x32_bf16 v[8:11], v[208:211], v[184:187], v[8:11]
	v_exp_f32_e32 v68, v68
	v_mfma_f32_16x16x32_bf16 v[40:43], v[208:211], v[192:195], v[40:43]
	ds_read_b64_tr_b16 v[200:201], v176 offset:24576
	ds_read_b64_tr_b16 v[202:203], v176 offset:28672
	v_exp_f32_e32 v69, v69
	v_mfma_f32_16x16x32_bf16 v[12:15], v[212:215], v[184:187], v[12:15]
	v_exp_f32_e32 v70, v70
	v_mfma_f32_16x16x32_bf16 v[44:47], v[212:215], v[192:195], v[44:47]
	ds_read_b64_tr_b16 v[204:205], v177 offset:24576
	ds_read_b64_tr_b16 v[206:207], v177 offset:28672
	v_exp_f32_e32 v71, v71
	s_waitcnt lgkmcnt(8)
	v_mfma_f32_16x16x32_bf16 v[16:19], v[230:233], v[184:187], v[16:19]
	v_exp_f32_e32 v72, v72
	v_mfma_f32_16x16x32_bf16 v[48:51], v[230:233], v[192:195], v[48:51]
	ds_read_b64_tr_b16 v[208:209], v178 offset:24576
	ds_read_b64_tr_b16 v[210:211], v178 offset:28672
	v_exp_f32_e32 v73, v73
	v_mfma_f32_16x16x32_bf16 v[20:23], v[234:237], v[184:187], v[20:23]
	v_exp_f32_e32 v74, v74
	v_mfma_f32_16x16x32_bf16 v[52:55], v[234:237], v[192:195], v[52:55]
	ds_read_b64_tr_b16 v[212:213], v179 offset:24576
	ds_read_b64_tr_b16 v[214:215], v179 offset:28672
	v_exp_f32_e32 v75, v75
	s_waitcnt lgkmcnt(8)
	v_mfma_f32_16x16x32_bf16 v[24:27], v[238:241], v[184:187], v[24:27]
	v_exp_f32_e32 v76, v76
	v_mfma_f32_16x16x32_bf16 v[56:59], v[238:241], v[192:195], v[56:59]
	ds_read_b64_tr_b16 v[230:231], v180 offset:24576
	ds_read_b64_tr_b16 v[232:233], v180 offset:28672
	v_exp_f32_e32 v77, v77
	v_mfma_f32_16x16x32_bf16 v[28:31], v[242:245], v[184:187], v[28:31]
	v_exp_f32_e32 v78, v78
	v_mfma_f32_16x16x32_bf16 v[60:63], v[242:245], v[192:195], v[60:63]
	ds_read_b64_tr_b16 v[234:235], v182 offset:24576
	ds_read_b64_tr_b16 v[236:237], v182 offset:28672
	v_exp_f32_e32 v79, v79
	s_waitcnt lgkmcnt(8)
; __device__ __forceinline__ void partialSM(f32x16& p0, f32x16& p1, float& m_reg, float& mn, float& alpha) {
;     ...
;   for (int r = 0; r < 16; ++r) p0[r] = __builtin_amdgcn_exp2f(p0[r]);
; }
; __device__ __forceinline__ void finishSM(f32x16& p0, f32x16& p1, float alpha, float& l_reg, bf16x8& pa0, bf16x8& pa1, bf16x8& pa2, bf16x8& pa3) {
; #pragma unroll
;   for (int r = 0; r < 16; ++r) p1[r] = __builtin_amdgcn_exp2f(p1[r]);
;   float ps = 0;
; #pragma unroll
;   for (int r = 0; r < 16; ++r) ps += p0[r];
; #pragma unroll
;   for (int r = 0; r < 16; ++r) ps += p1[r];
;   { auto rr = __builtin_amdgcn_permlane32_swap(__float_as_uint(ps), __float_as_uint(ps), false, false);
;     ps = __uint_as_float(rr[0]) + __uint_as_float(rr[1]); }
;   l_reg = l_reg * alpha + ps;
;     ...
;   PK4(p0, 0, pa0); PK4(p0, 8, pa1); PK4(p1, 0, pa2); PK4(p1, 8, pa3);
;     ...
; }
; __device__ __forceinline__ void qkt(f32x16& p0, f32x16& p1, const bf16* Ks, const bf16x8* qr, int r32, int hi) {
;   p0 = f32x16{}; p1 = f32x16{};
; #pragma unroll
;   for (int d0 = 0; d0 < 8; ++d0) { int cb = (d0 * 16 + hi * 8) * 2;
;     bf16x8 b0 = *reinterpret_cast<const bf16x8*>((const char*)Ks + KSWZ(r32, cb));
;     bf16x8 b1 = *reinterpret_cast<const bf16x8*>((const char*)Ks + KSWZ(32 + r32, cb));
;     p0 = __builtin_amdgcn_mfma_f32_32x32x16_bf16(b0, qr[d0], p0, 0, 0, 0);
;     p1 = __builtin_amdgcn_mfma_f32_32x32x16_bf16(b1, qr[d0], p1, 0, 0, 0); }
; }
; __device__ __forceinline__ int v_st(int k, int c) { const int kk = (k & ~0xC) | ((k & 4) << 1) | ((k & 8) >> 1); return ((kk >> 3) * 4 + (c >> 5)) * 512 + ((kk & 7) * 32 + (c & 31)) * 2; }
; __device__ __forceinline__ int v_rd_base(int lane) { return ((lane & 3) << 3) | (((lane >> 2) & 3) << 6) | (((lane >> 4) & 1) << 5) | (((lane >> 5) & 1) << 8); }
; template <int OFF> __device__ __forceinline__ s16x4 tr_read(int vb) {
;   s16x4 r; asm volatile("ds_read_b64_tr_b16 %0, %1 offset:%2" : "=&v"(r) : "v"(vb), "i"(OFF) : "memory"); return r;
; }
; template <int D0> __device__ __forceinline__ void pv_one(f32x16& od, int vb, bf16x8 pa0, bf16x8 pa1, bf16x8 pa2, bf16x8 pa3) {
;   const s16x4 l0 = tr_read<v_rd_off(D0, 0, 0)>(vb), h0 = tr_read<v_rd_off(D0, 0, 1)>(vb), l1 = tr_read<v_rd_off(D0, 1, 0)>(vb), h1 = tr_read<v_rd_off(D0, 1, 1)>(vb);
	v_mfma_f32_16x16x32_bf16 v[0:3], v[200:203], v[188:191], v[0:3]
	v_exp_f32_e32 v80, v80
	v_mfma_f32_16x16x32_bf16 v[32:35], v[200:203], v[196:199], v[32:35]
	ds_read_b64_tr_b16 v[238:239], v216 offset:24576
	ds_read_b64_tr_b16 v[240:241], v216 offset:28672
	ds_read_b128 v[200:203], v172 offset:49152
	v_exp_f32_e32 v81, v81
	v_mfma_f32_16x16x32_bf16 v[4:7], v[204:207], v[188:191], v[4:7]
	v_exp_f32_e32 v82, v82
	v_mfma_f32_16x16x32_bf16 v[36:39], v[204:207], v[196:199], v[36:39]
	ds_read_b64_tr_b16 v[242:243], v217 offset:24576
	ds_read_b64_tr_b16 v[244:245], v217 offset:28672
	ds_read_b128 v[204:207], v172 offset:53248
	v_exp_f32_e32 v83, v83
	s_waitcnt lgkmcnt(10)
	v_mfma_f32_16x16x32_bf16 v[8:11], v[208:211], v[188:191], v[8:11]
	v_exp_f32_e32 v84, v84
	v_mfma_f32_16x16x32_bf16 v[40:43], v[208:211], v[196:199], v[40:43]
	ds_read_b128 v[208:211], v172 offset:57344
	v_exp_f32_e32 v85, v85
	v_mfma_f32_16x16x32_bf16 v[12:15], v[212:215], v[188:191], v[12:15]
	v_exp_f32_e32 v86, v86
	v_mfma_f32_16x16x32_bf16 v[44:47], v[212:215], v[196:199], v[44:47]
	ds_read_b128 v[212:215], v172 offset:61440
	v_exp_f32_e32 v87, v87
	s_waitcnt lgkmcnt(8)
	v_mfma_f32_16x16x32_bf16 v[16:19], v[230:233], v[188:191], v[16:19]
	v_exp_f32_e32 v88, v88
	v_mfma_f32_16x16x32_bf16 v[48:51], v[230:233], v[196:199], v[48:51]
	ds_read_b128 v[230:233], v173 offset:49152
	v_exp_f32_e32 v89, v89
	v_mfma_f32_16x16x32_bf16 v[20:23], v[234:237], v[188:191], v[20:23]
	v_exp_f32_e32 v90, v90
	v_mfma_f32_16x16x32_bf16 v[52:55], v[234:237], v[196:199], v[52:55]
	ds_read_b128 v[234:237], v173 offset:53248
	v_exp_f32_e32 v91, v91
	s_waitcnt lgkmcnt(5)
	v_mfma_f32_16x16x32_bf16 v[24:27], v[238:241], v[188:191], v[24:27]
	v_exp_f32_e32 v92, v92
	v_mfma_f32_16x16x32_bf16 v[56:59], v[238:241], v[196:199], v[56:59]
	ds_read_b128 v[238:241], v173 offset:57344
	v_exp_f32_e32 v93, v93
	v_mfma_f32_16x16x32_bf16 v[28:31], v[242:245], v[188:191], v[28:31]
	v_exp_f32_e32 v94, v94
	v_mfma_f32_16x16x32_bf16 v[60:63], v[242:245], v[196:199], v[60:63]
	ds_read_b128 v[242:245], v173 offset:61440
	v_exp_f32_e32 v95, v95
	s_waitcnt vmcnt(4)
	s_barrier
	s_waitcnt lgkmcnt(6)
	v_mfma_f32_16x16x32_bf16 v[128:131], v[200:203], v[96:99], 0
	v_add_f32_e32 v169, v169, v64
	s_add_i32 m0, s32, 0x8000
	v_mfma_f32_16x16x32_bf16 v[132:135], v[200:203], v[112:115], 0
	ds_read_b128 v[200:203], v174 offset:49152
	v_add_f32_e32 v169, v169, v65
	v_cvt_pk_bf16_f32 v184, v64, v65
	global_load_lds_dwordx4 v183, s[98:99]
	v_mfma_f32_16x16x32_bf16 v[136:139], v[204:207], v[96:99], 0
	v_add_f32_e32 v169, v169, v66
	v_mfma_f32_16x16x32_bf16 v[140:143], v[204:207], v[112:115], 0
	ds_read_b128 v[204:207], v174 offset:53248
	v_add_f32_e32 v169, v169, v67
	v_cvt_pk_bf16_f32 v185, v66, v67
	s_waitcnt lgkmcnt(6)
	v_mfma_f32_16x16x32_bf16 v[144:147], v[208:211], v[96:99], 0
	v_add_f32_e32 v222, v222, v68
	s_add_i32 m0, s32, 0xa000
	v_mfma_f32_16x16x32_bf16 v[148:151], v[208:211], v[112:115], 0
	ds_read_b128 v[208:211], v174 offset:57344
	v_add_f32_e32 v222, v222, v69
	v_cvt_pk_bf16_f32 v186, v72, v73
	global_load_lds_dwordx4 v246, s[98:99]
	s_add_u32 s98, s98, 0x150000
	s_addc_u32 s99, s99, 0
	v_mfma_f32_16x16x32_bf16 v[152:155], v[212:215], v[96:99], 0
	v_add_f32_e32 v222, v222, v70
	v_mfma_f32_16x16x32_bf16 v[156:159], v[212:215], v[112:115], 0
	ds_read_b128 v[212:215], v174 offset:61440
	v_add_f32_e32 v222, v222, v71
	v_cvt_pk_bf16_f32 v187, v74, v75
	s_waitcnt lgkmcnt(6)
	v_mfma_f32_16x16x32_bf16 v[128:131], v[230:233], v[100:103], v[128:131]
	v_add_f32_e32 v169, v169, v72
	s_add_i32 m0, s32, 0x10000
	v_mfma_f32_16x16x32_bf16 v[132:135], v[230:233], v[116:119], v[132:135]
	ds_read_b128 v[230:233], v175 offset:49152
	v_add_f32_e32 v169, v169, v73
	v_cvt_pk_bf16_f32 v188, v80, v81
	global_load_lds_dwordx4 v181, s[0:1]
	v_mfma_f32_16x16x32_bf16 v[136:139], v[234:237], v[100:103], v[136:139]
	v_add_f32_e32 v169, v169, v74
	v_mfma_f32_16x16x32_bf16 v[140:143], v[234:237], v[116:119], v[140:143]
	ds_read_b128 v[234:237], v175 offset:53248
	v_add_f32_e32 v169, v169, v75
	v_cvt_pk_bf16_f32 v189, v82, v83
	s_waitcnt lgkmcnt(6)
	v_mfma_f32_16x16x32_bf16 v[144:147], v[238:241], v[100:103], v[144:147]
	v_add_f32_e32 v222, v222, v76
	s_add_i32 m0, s32, 0x12000
	v_mfma_f32_16x16x32_bf16 v[148:151], v[238:241], v[116:119], v[148:151]
	ds_read_b128 v[238:241], v175 offset:57344
	v_add_f32_e32 v222, v222, v77
	v_cvt_pk_bf16_f32 v190, v88, v89
	global_load_lds_dwordx4 v247, s[0:1]
	s_add_u32 s0, s0, 0x150000
	s_addc_u32 s1, s1, 0
	v_mfma_f32_16x16x32_bf16 v[152:155], v[242:245], v[100:103], v[152:155]
	v_add_f32_e32 v222, v222, v78
	v_mfma_f32_16x16x32_bf16 v[156:159], v[242:245], v[116:119], v[156:159]
	ds_read_b128 v[242:245], v175 offset:61440
	v_add_f32_e32 v222, v222, v79
	v_cvt_pk_bf16_f32 v191, v90, v91
	s_waitcnt lgkmcnt(6)
	v_mfma_f32_16x16x32_bf16 v[128:131], v[200:203], v[104:107], v[128:131]
	v_add_f32_e32 v169, v169, v80
	v_mfma_f32_16x16x32_bf16 v[132:135], v[200:203], v[120:123], v[132:135]
	v_add_f32_e32 v169, v169, v81
	v_cvt_pk_bf16_f32 v192, v68, v69
	v_mfma_f32_16x16x32_bf16 v[136:139], v[204:207], v[104:107], v[136:139]
	v_add_f32_e32 v169, v169, v82
	v_mfma_f32_16x16x32_bf16 v[140:143], v[204:207], v[120:123], v[140:143]
	v_add_f32_e32 v169, v169, v83
	v_cvt_pk_bf16_f32 v193, v70, v71
	s_waitcnt lgkmcnt(4)
; __device__ __forceinline__ void partialSM(f32x16& p0, f32x16& p1, float& m_reg, float& mn, float& alpha) {
;     ...
;   for (int r = 0; r < 16; ++r) p0[r] = __builtin_amdgcn_exp2f(p0[r]);
; }
; __device__ __forceinline__ void finishSM(f32x16& p0, f32x16& p1, float alpha, float& l_reg, bf16x8& pa0, bf16x8& pa1, bf16x8& pa2, bf16x8& pa3) {
; #pragma unroll
;   for (int r = 0; r < 16; ++r) p1[r] = __builtin_amdgcn_exp2f(p1[r]);
;   float ps = 0;
; #pragma unroll
;   for (int r = 0; r < 16; ++r) ps += p0[r];
; #pragma unroll
;   for (int r = 0; r < 16; ++r) ps += p1[r];
;   { auto rr = __builtin_amdgcn_permlane32_swap(__float_as_uint(ps), __float_as_uint(ps), false, false);
;     ps = __uint_as_float(rr[0]) + __uint_as_float(rr[1]); }
;   l_reg = l_reg * alpha + ps;
;     ...
;   PK4(p0, 0, pa0); PK4(p0, 8, pa1); PK4(p1, 0, pa2); PK4(p1, 8, pa3);
;     ...
; }
; __device__ __forceinline__ void qkt(f32x16& p0, f32x16& p1, const bf16* Ks, const bf16x8* qr, int r32, int hi) {
;   p0 = f32x16{}; p1 = f32x16{};
; #pragma unroll
;   for (int d0 = 0; d0 < 8; ++d0) { int cb = (d0 * 16 + hi * 8) * 2;
;     bf16x8 b0 = *reinterpret_cast<const bf16x8*>((const char*)Ks + KSWZ(r32, cb));
;     bf16x8 b1 = *reinterpret_cast<const bf16x8*>((const char*)Ks + KSWZ(32 + r32, cb));
;     p0 = __builtin_amdgcn_mfma_f32_32x32x16_bf16(b0, qr[d0], p0, 0, 0, 0);
;     p1 = __builtin_amdgcn_mfma_f32_32x32x16_bf16(b1, qr[d0], p1, 0, 0, 0); }
; }
; __device__ __forceinline__ int v_st(int k, int c) { const int kk = (k & ~0xC) | ((k & 4) << 1) | ((k & 8) >> 1); return ((kk >> 3) * 4 + (c >> 5)) * 512 + ((kk & 7) * 32 + (c & 31)) * 2; }
; __device__ __forceinline__ int v_rd_base(int lane) { return ((lane & 3) << 3) | (((lane >> 2) & 3) << 6) | (((lane >> 4) & 1) << 5) | (((lane >> 5) & 1) << 8); }
; template <int OFF> __device__ __forceinline__ s16x4 tr_read(int vb) {
;   s16x4 r; asm volatile("ds_read_b64_tr_b16 %0, %1 offset:%2" : "=&v"(r) : "v"(vb), "i"(OFF) : "memory"); return r;
; }
; template <int D0> __device__ __forceinline__ void pv_one(f32x16& od, int vb, bf16x8 pa0, bf16x8 pa1, bf16x8 pa2, bf16x8 pa3) {
;   const s16x4 l0 = tr_read<v_rd_off(D0, 0, 0)>(vb), h0 = tr_read<v_rd_off(D0, 0, 1)>(vb), l1 = tr_read<v_rd_off(D0, 1, 0)>(vb), h1 = tr_read<v_rd_off(D0, 1, 1)>(vb);
	v_mfma_f32_16x16x32_bf16 v[144:147], v[208:211], v[104:107], v[144:147]
	ds_read_b64_tr_b16 v[200:201], v176 offset:32768
	ds_read_b64_tr_b16 v[202:203], v176 offset:36864
	v_add_f32_e32 v222, v222, v84
	v_mfma_f32_16x16x32_bf16 v[148:151], v[208:211], v[120:123], v[148:151]
	v_add_f32_e32 v222, v222, v85
	v_cvt_pk_bf16_f32 v194, v76, v77
	v_mfma_f32_16x16x32_bf16 v[152:155], v[212:215], v[104:107], v[152:155]
	ds_read_b64_tr_b16 v[204:205], v177 offset:32768
	ds_read_b64_tr_b16 v[206:207], v177 offset:36864
	v_add_f32_e32 v222, v222, v86
	v_mfma_f32_16x16x32_bf16 v[156:159], v[212:215], v[120:123], v[156:159]
	v_add_f32_e32 v222, v222, v87
	v_cvt_pk_bf16_f32 v195, v78, v79
	s_waitcnt lgkmcnt(6)
	v_mfma_f32_16x16x32_bf16 v[128:131], v[230:233], v[108:111], v[128:131]
	ds_read_b64_tr_b16 v[208:209], v178 offset:32768
	ds_read_b64_tr_b16 v[210:211], v178 offset:36864
	v_add_f32_e32 v169, v169, v88
	v_mfma_f32_16x16x32_bf16 v[132:135], v[230:233], v[124:127], v[132:135]
	v_add_f32_e32 v169, v169, v89
	v_cvt_pk_bf16_f32 v196, v84, v85
	v_mfma_f32_16x16x32_bf16 v[136:139], v[234:237], v[108:111], v[136:139]
	ds_read_b64_tr_b16 v[212:213], v179 offset:32768
	ds_read_b64_tr_b16 v[214:215], v179 offset:36864
	v_add_f32_e32 v169, v169, v90
	v_mfma_f32_16x16x32_bf16 v[140:143], v[234:237], v[124:127], v[140:143]
	v_add_f32_e32 v169, v169, v91
	v_cvt_pk_bf16_f32 v197, v86, v87
	s_waitcnt lgkmcnt(8)
	v_mfma_f32_16x16x32_bf16 v[144:147], v[238:241], v[108:111], v[144:147]
	ds_read_b64_tr_b16 v[230:231], v180 offset:32768
	ds_read_b64_tr_b16 v[232:233], v180 offset:36864
	v_add_f32_e32 v222, v222, v92
	v_mfma_f32_16x16x32_bf16 v[148:151], v[238:241], v[124:127], v[148:151]
	v_add_f32_e32 v222, v222, v93
	v_cvt_pk_bf16_f32 v198, v92, v93
	v_mfma_f32_16x16x32_bf16 v[152:155], v[242:245], v[108:111], v[152:155]
	ds_read_b64_tr_b16 v[234:235], v182 offset:32768
	ds_read_b64_tr_b16 v[236:237], v182 offset:36864
	v_add_f32_e32 v222, v222, v94
	v_mfma_f32_16x16x32_bf16 v[156:159], v[242:245], v[124:127], v[156:159]
	v_add_f32_e32 v222, v222, v95
	v_cvt_pk_bf16_f32 v199, v94, v95
	s_waitcnt lgkmcnt(8)
	v_mfma_f32_16x16x32_bf16 v[0:3], v[200:203], v[184:187], v[0:3]
	v_exp_f32_e32 v128, v128
	v_mfma_f32_16x16x32_bf16 v[32:35], v[200:203], v[192:195], v[32:35]
	ds_read_b64_tr_b16 v[238:239], v216 offset:32768
	ds_read_b64_tr_b16 v[240:241], v216 offset:36864
	v_exp_f32_e32 v129, v129
	v_mfma_f32_16x16x32_bf16 v[4:7], v[204:207], v[184:187], v[4:7]
	v_exp_f32_e32 v130, v130
	v_mfma_f32_16x16x32_bf16 v[36:39], v[204:207], v[192:195], v[36:39]
	ds_read_b64_tr_b16 v[242:243], v217 offset:32768
	ds_read_b64_tr_b16 v[244:245], v217 offset:36864
	v_exp_f32_e32 v131, v131
	s_waitcnt lgkmcnt(8)
	v_mfma_f32_16x16x32_bf16 v[8:11], v[208:211], v[184:187], v[8:11]
	v_exp_f32_e32 v132, v132
	v_mfma_f32_16x16x32_bf16 v[40:43], v[208:211], v[192:195], v[40:43]
	ds_read_b64_tr_b16 v[200:201], v176 offset:40960
	ds_read_b64_tr_b16 v[202:203], v176 offset:45056
	v_exp_f32_e32 v133, v133
	v_mfma_f32_16x16x32_bf16 v[12:15], v[212:215], v[184:187], v[12:15]
	v_exp_f32_e32 v134, v134
	v_mfma_f32_16x16x32_bf16 v[44:47], v[212:215], v[192:195], v[44:47]
	ds_read_b64_tr_b16 v[204:205], v177 offset:40960
	ds_read_b64_tr_b16 v[206:207], v177 offset:45056
	v_exp_f32_e32 v135, v135
	s_waitcnt lgkmcnt(8)
	v_mfma_f32_16x16x32_bf16 v[16:19], v[230:233], v[184:187], v[16:19]
	v_exp_f32_e32 v136, v136
	v_mfma_f32_16x16x32_bf16 v[48:51], v[230:233], v[192:195], v[48:51]
	ds_read_b64_tr_b16 v[208:209], v178 offset:40960
	ds_read_b64_tr_b16 v[210:211], v178 offset:45056
	v_exp_f32_e32 v137, v137
	v_mfma_f32_16x16x32_bf16 v[20:23], v[234:237], v[184:187], v[20:23]
	v_exp_f32_e32 v138, v138
	v_mfma_f32_16x16x32_bf16 v[52:55], v[234:237], v[192:195], v[52:55]
	ds_read_b64_tr_b16 v[212:213], v179 offset:40960
	ds_read_b64_tr_b16 v[214:215], v179 offset:45056
	v_exp_f32_e32 v139, v139
	s_waitcnt lgkmcnt(8)
	v_mfma_f32_16x16x32_bf16 v[24:27], v[238:241], v[184:187], v[24:27]
	v_exp_f32_e32 v140, v140
	v_mfma_f32_16x16x32_bf16 v[56:59], v[238:241], v[192:195], v[56:59]
	ds_read_b64_tr_b16 v[230:231], v180 offset:40960
	ds_read_b64_tr_b16 v[232:233], v180 offset:45056
	v_exp_f32_e32 v141, v141
	v_mfma_f32_16x16x32_bf16 v[28:31], v[242:245], v[184:187], v[28:31]
	v_exp_f32_e32 v142, v142
	v_mfma_f32_16x16x32_bf16 v[60:63], v[242:245], v[192:195], v[60:63]
	ds_read_b64_tr_b16 v[234:235], v182 offset:40960
	ds_read_b64_tr_b16 v[236:237], v182 offset:45056
	v_exp_f32_e32 v143, v143
	s_waitcnt lgkmcnt(8)
	v_mfma_f32_16x16x32_bf16 v[0:3], v[200:203], v[188:191], v[0:3]
	v_exp_f32_e32 v144, v144
	v_mfma_f32_16x16x32_bf16 v[32:35], v[200:203], v[196:199], v[32:35]
	ds_read_b64_tr_b16 v[238:239], v216 offset:40960
	ds_read_b64_tr_b16 v[240:241], v216 offset:45056
	ds_read_b128 v[200:203], v172 offset:0
	v_exp_f32_e32 v145, v145
	v_mfma_f32_16x16x32_bf16 v[4:7], v[204:207], v[188:191], v[4:7]
	v_exp_f32_e32 v146, v146
	v_mfma_f32_16x16x32_bf16 v[36:39], v[204:207], v[196:199], v[36:39]
	ds_read_b64_tr_b16 v[242:243], v217 offset:40960
	ds_read_b64_tr_b16 v[244:245], v217 offset:45056
	ds_read_b128 v[204:207], v172 offset:4096
	v_exp_f32_e32 v147, v147
	s_waitcnt lgkmcnt(10)
	v_mfma_f32_16x16x32_bf16 v[8:11], v[208:211], v[188:191], v[8:11]
	v_exp_f32_e32 v148, v148
	v_mfma_f32_16x16x32_bf16 v[40:43], v[208:211], v[196:199], v[40:43]
	ds_read_b128 v[208:211], v172 offset:8192
	v_exp_f32_e32 v149, v149
	v_mfma_f32_16x16x32_bf16 v[12:15], v[212:215], v[188:191], v[12:15]
	v_exp_f32_e32 v150, v150
	v_mfma_f32_16x16x32_bf16 v[44:47], v[212:215], v[196:199], v[44:47]
	ds_read_b128 v[212:215], v172 offset:12288
	v_exp_f32_e32 v151, v151
	s_waitcnt lgkmcnt(8)
	v_mfma_f32_16x16x32_bf16 v[16:19], v[230:233], v[188:191], v[16:19]
	v_exp_f32_e32 v152, v152
	v_mfma_f32_16x16x32_bf16 v[48:51], v[230:233], v[196:199], v[48:51]
	ds_read_b128 v[230:233], v173 offset:0
	v_exp_f32_e32 v153, v153
	v_mfma_f32_16x16x32_bf16 v[20:23], v[234:237], v[188:191], v[20:23]
	v_exp_f32_e32 v154, v154
	v_mfma_f32_16x16x32_bf16 v[52:55], v[234:237], v[196:199], v[52:55]
	ds_read_b128 v[234:237], v173 offset:4096
	v_exp_f32_e32 v155, v155
	s_waitcnt lgkmcnt(5)
	v_mfma_f32_16x16x32_bf16 v[24:27], v[238:241], v[188:191], v[24:27]
	v_exp_f32_e32 v156, v156
	v_mfma_f32_16x16x32_bf16 v[56:59], v[238:241], v[196:199], v[56:59]
	ds_read_b128 v[238:241], v173 offset:8192
	v_exp_f32_e32 v157, v157
	v_mfma_f32_16x16x32_bf16 v[28:31], v[242:245], v[188:191], v[28:31]
	v_exp_f32_e32 v158, v158
	v_mfma_f32_16x16x32_bf16 v[60:63], v[242:245], v[196:199], v[60:63]
	ds_read_b128 v[242:245], v173 offset:12288
	v_exp_f32_e32 v159, v159
	s_waitcnt vmcnt(4)
	s_barrier
; __device__ __forceinline__ void partialSM(f32x16& p0, f32x16& p1, float& m_reg, float& mn, float& alpha) {
;     ...
;   for (int r = 0; r < 16; ++r) p0[r] = __builtin_amdgcn_exp2f(p0[r]);
; }
; __device__ __forceinline__ void finishSM(f32x16& p0, f32x16& p1, float alpha, float& l_reg, bf16x8& pa0, bf16x8& pa1, bf16x8& pa2, bf16x8& pa3) {
; #pragma unroll
;   for (int r = 0; r < 16; ++r) p1[r] = __builtin_amdgcn_exp2f(p1[r]);
;   float ps = 0;
; #pragma unroll
;   for (int r = 0; r < 16; ++r) ps += p0[r];
; #pragma unroll
;   for (int r = 0; r < 16; ++r) ps += p1[r];
;   { auto rr = __builtin_amdgcn_permlane32_swap(__float_as_uint(ps), __float_as_uint(ps), false, false);
;     ps = __uint_as_float(rr[0]) + __uint_as_float(rr[1]); }
;   l_reg = l_reg * alpha + ps;
;     ...
;   PK4(p0, 0, pa0); PK4(p0, 8, pa1); PK4(p1, 0, pa2); PK4(p1, 8, pa3);
;     ...
; }
; __device__ __forceinline__ void qkt(f32x16& p0, f32x16& p1, const bf16* Ks, const bf16x8* qr, int r32, int hi) {
;   p0 = f32x16{}; p1 = f32x16{};
; #pragma unroll
;   for (int d0 = 0; d0 < 8; ++d0) { int cb = (d0 * 16 + hi * 8) * 2;
;     bf16x8 b0 = *reinterpret_cast<const bf16x8*>((const char*)Ks + KSWZ(r32, cb));
;     bf16x8 b1 = *reinterpret_cast<const bf16x8*>((const char*)Ks + KSWZ(32 + r32, cb));
;     p0 = __builtin_amdgcn_mfma_f32_32x32x16_bf16(b0, qr[d0], p0, 0, 0, 0);
;     p1 = __builtin_amdgcn_mfma_f32_32x32x16_bf16(b1, qr[d0], p1, 0, 0, 0); }
; }
; __device__ __forceinline__ int v_st(int k, int c) { const int kk = (k & ~0xC) | ((k & 4) << 1) | ((k & 8) >> 1); return ((kk >> 3) * 4 + (c >> 5)) * 512 + ((kk & 7) * 32 + (c & 31)) * 2; }
; __device__ __forceinline__ int v_rd_base(int lane) { return ((lane & 3) << 3) | (((lane >> 2) & 3) << 6) | (((lane >> 4) & 1) << 5) | (((lane >> 5) & 1) << 8); }
; template <int OFF> __device__ __forceinline__ s16x4 tr_read(int vb) {
;   s16x4 r; asm volatile("ds_read_b64_tr_b16 %0, %1 offset:%2" : "=&v"(r) : "v"(vb), "i"(OFF) : "memory"); return r;
; }
; template <int D0> __device__ __forceinline__ void pv_one(f32x16& od, int vb, bf16x8 pa0, bf16x8 pa1, bf16x8 pa2, bf16x8 pa3) {
;   const s16x4 l0 = tr_read<v_rd_off(D0, 0, 0)>(vb), h0 = tr_read<v_rd_off(D0, 0, 1)>(vb), l1 = tr_read<v_rd_off(D0, 1, 0)>(vb), h1 = tr_read<v_rd_off(D0, 1, 1)>(vb);
	s_waitcnt lgkmcnt(6)
	v_mfma_f32_16x16x32_bf16 v[64:67], v[200:203], v[96:99], 0
	v_add_f32_e32 v169, v169, v128
	s_add_i32 m0, s32, 0xc000
	v_mfma_f32_16x16x32_bf16 v[68:71], v[200:203], v[112:115], 0
	ds_read_b128 v[200:203], v174 offset:0
	v_add_f32_e32 v169, v169, v129
	v_cvt_pk_bf16_f32 v184, v128, v129
	global_load_lds_dwordx4 v183, s[98:99]
	v_mfma_f32_16x16x32_bf16 v[72:75], v[204:207], v[96:99], 0
	v_add_f32_e32 v169, v169, v130
	v_mfma_f32_16x16x32_bf16 v[76:79], v[204:207], v[112:115], 0
	ds_read_b128 v[204:207], v174 offset:4096
	v_add_f32_e32 v169, v169, v131
	v_cvt_pk_bf16_f32 v185, v130, v131
	s_waitcnt lgkmcnt(6)
	v_mfma_f32_16x16x32_bf16 v[80:83], v[208:211], v[96:99], 0
	v_add_f32_e32 v222, v222, v132
	s_add_i32 m0, s32, 0xe000
	v_mfma_f32_16x16x32_bf16 v[84:87], v[208:211], v[112:115], 0
	ds_read_b128 v[208:211], v174 offset:8192
	v_add_f32_e32 v222, v222, v133
	v_cvt_pk_bf16_f32 v186, v136, v137
	global_load_lds_dwordx4 v246, s[98:99]
	s_add_u32 s98, s98, 0x150000
	s_addc_u32 s99, s99, 0
	v_mfma_f32_16x16x32_bf16 v[88:91], v[212:215], v[96:99], 0
	v_add_f32_e32 v222, v222, v134
	v_mfma_f32_16x16x32_bf16 v[92:95], v[212:215], v[112:115], 0
	ds_read_b128 v[212:215], v174 offset:12288
	v_add_f32_e32 v222, v222, v135
	v_cvt_pk_bf16_f32 v187, v138, v139
	s_waitcnt lgkmcnt(6)
	v_mfma_f32_16x16x32_bf16 v[64:67], v[230:233], v[100:103], v[64:67]
	v_add_f32_e32 v169, v169, v136
	s_add_i32 m0, s32, 0x14000
	v_mfma_f32_16x16x32_bf16 v[68:71], v[230:233], v[116:119], v[68:71]
	ds_read_b128 v[230:233], v175 offset:0
	v_add_f32_e32 v169, v169, v137
	v_cvt_pk_bf16_f32 v188, v144, v145
	global_load_lds_dwordx4 v181, s[0:1]
	v_mfma_f32_16x16x32_bf16 v[72:75], v[234:237], v[100:103], v[72:75]
	v_add_f32_e32 v169, v169, v138
	v_mfma_f32_16x16x32_bf16 v[76:79], v[234:237], v[116:119], v[76:79]
	ds_read_b128 v[234:237], v175 offset:4096
	v_add_f32_e32 v169, v169, v139
	v_cvt_pk_bf16_f32 v189, v146, v147
	s_waitcnt lgkmcnt(6)
	v_mfma_f32_16x16x32_bf16 v[80:83], v[238:241], v[100:103], v[80:83]
	v_add_f32_e32 v222, v222, v140
	s_add_i32 m0, s32, 0x16000
	v_mfma_f32_16x16x32_bf16 v[84:87], v[238:241], v[116:119], v[84:87]
	ds_read_b128 v[238:241], v175 offset:8192
	v_add_f32_e32 v222, v222, v141
	v_cvt_pk_bf16_f32 v190, v152, v153
	global_load_lds_dwordx4 v247, s[0:1]
	s_add_u32 s0, s0, 0x150000
	s_addc_u32 s1, s1, 0
	v_mfma_f32_16x16x32_bf16 v[88:91], v[242:245], v[100:103], v[88:91]
	v_add_f32_e32 v222, v222, v142
	v_mfma_f32_16x16x32_bf16 v[92:95], v[242:245], v[116:119], v[92:95]
	ds_read_b128 v[242:245], v175 offset:12288
	v_add_f32_e32 v222, v222, v143
	v_cvt_pk_bf16_f32 v191, v154, v155
	s_waitcnt lgkmcnt(6)
	v_mfma_f32_16x16x32_bf16 v[64:67], v[200:203], v[104:107], v[64:67]
	v_add_f32_e32 v169, v169, v144
	v_mfma_f32_16x16x32_bf16 v[68:71], v[200:203], v[120:123], v[68:71]
	v_add_f32_e32 v169, v169, v145
	v_cvt_pk_bf16_f32 v192, v132, v133
	v_mfma_f32_16x16x32_bf16 v[72:75], v[204:207], v[104:107], v[72:75]
	v_add_f32_e32 v169, v169, v146
	v_mfma_f32_16x16x32_bf16 v[76:79], v[204:207], v[120:123], v[76:79]
	v_add_f32_e32 v169, v169, v147
	v_cvt_pk_bf16_f32 v193, v134, v135
	s_waitcnt lgkmcnt(4)
	v_mfma_f32_16x16x32_bf16 v[80:83], v[208:211], v[104:107], v[80:83]
	ds_read_b64_tr_b16 v[200:201], v176 offset:49152
	ds_read_b64_tr_b16 v[202:203], v176 offset:53248
	v_add_f32_e32 v222, v222, v148
	v_mfma_f32_16x16x32_bf16 v[84:87], v[208:211], v[120:123], v[84:87]
	v_add_f32_e32 v222, v222, v149
	v_cvt_pk_bf16_f32 v194, v140, v141
	v_mfma_f32_16x16x32_bf16 v[88:91], v[212:215], v[104:107], v[88:91]
	ds_read_b64_tr_b16 v[204:205], v177 offset:49152
	ds_read_b64_tr_b16 v[206:207], v177 offset:53248
	v_add_f32_e32 v222, v222, v150
	v_mfma_f32_16x16x32_bf16 v[92:95], v[212:215], v[120:123], v[92:95]
	v_add_f32_e32 v222, v222, v151
	v_cvt_pk_bf16_f32 v195, v142, v143
	s_waitcnt lgkmcnt(6)
	v_mfma_f32_16x16x32_bf16 v[64:67], v[230:233], v[108:111], v[64:67]
	ds_read_b64_tr_b16 v[208:209], v178 offset:49152
	ds_read_b64_tr_b16 v[210:211], v178 offset:53248
	v_add_f32_e32 v169, v169, v152
	v_mfma_f32_16x16x32_bf16 v[68:71], v[230:233], v[124:127], v[68:71]
	v_add_f32_e32 v169, v169, v153
	v_cvt_pk_bf16_f32 v196, v148, v149
	v_mfma_f32_16x16x32_bf16 v[72:75], v[234:237], v[108:111], v[72:75]
	ds_read_b64_tr_b16 v[212:213], v179 offset:49152
	ds_read_b64_tr_b16 v[214:215], v179 offset:53248
	v_add_f32_e32 v169, v169, v154
	v_mfma_f32_16x16x32_bf16 v[76:79], v[234:237], v[124:127], v[76:79]
	v_add_f32_e32 v169, v169, v155
	v_cvt_pk_bf16_f32 v197, v150, v151
	s_waitcnt lgkmcnt(8)
	v_mfma_f32_16x16x32_bf16 v[80:83], v[238:241], v[108:111], v[80:83]
	ds_read_b64_tr_b16 v[230:231], v180 offset:49152
	ds_read_b64_tr_b16 v[232:233], v180 offset:53248
	v_add_f32_e32 v222, v222, v156
	v_mfma_f32_16x16x32_bf16 v[84:87], v[238:241], v[124:127], v[84:87]
	v_add_f32_e32 v222, v222, v157
	v_cvt_pk_bf16_f32 v198, v156, v157
	v_mfma_f32_16x16x32_bf16 v[88:91], v[242:245], v[108:111], v[88:91]
	ds_read_b64_tr_b16 v[234:235], v182 offset:49152
	ds_read_b64_tr_b16 v[236:237], v182 offset:53248
	v_add_f32_e32 v222, v222, v158
	v_mfma_f32_16x16x32_bf16 v[92:95], v[242:245], v[124:127], v[92:95]
	v_add_f32_e32 v222, v222, v159
	v_cvt_pk_bf16_f32 v199, v158, v159
	s_waitcnt lgkmcnt(8)
	v_mfma_f32_16x16x32_bf16 v[0:3], v[200:203], v[184:187], v[0:3]
	v_exp_f32_e32 v64, v64
	v_mfma_f32_16x16x32_bf16 v[32:35], v[200:203], v[192:195], v[32:35]
	ds_read_b64_tr_b16 v[238:239], v216 offset:49152
	ds_read_b64_tr_b16 v[240:241], v216 offset:53248
	v_exp_f32_e32 v65, v65
	v_mfma_f32_16x16x32_bf16 v[4:7], v[204:207], v[184:187], v[4:7]
	v_exp_f32_e32 v66, v66
	v_mfma_f32_16x16x32_bf16 v[36:39], v[204:207], v[192:195], v[36:39]
	ds_read_b64_tr_b16 v[242:243], v217 offset:49152
	ds_read_b64_tr_b16 v[244:245], v217 offset:53248
	v_exp_f32_e32 v67, v67
	s_waitcnt lgkmcnt(8)
; __device__ __forceinline__ void partialSM(f32x16& p0, f32x16& p1, float& m_reg, float& mn, float& alpha) {
;     ...
;   for (int r = 0; r < 16; ++r) p0[r] = __builtin_amdgcn_exp2f(p0[r]);
; }
; __device__ __forceinline__ void finishSM(f32x16& p0, f32x16& p1, float alpha, float& l_reg, bf16x8& pa0, bf16x8& pa1, bf16x8& pa2, bf16x8& pa3) {
; #pragma unroll
;   for (int r = 0; r < 16; ++r) p1[r] = __builtin_amdgcn_exp2f(p1[r]);
;   float ps = 0;
; #pragma unroll
;   for (int r = 0; r < 16; ++r) ps += p0[r];
; #pragma unroll
;   for (int r = 0; r < 16; ++r) ps += p1[r];
;   { auto rr = __builtin_amdgcn_permlane32_swap(__float_as_uint(ps), __float_as_uint(ps), false, false);
;     ps = __uint_as_float(rr[0]) + __uint_as_float(rr[1]); }
;   l_reg = l_reg * alpha + ps;
;     ...
;   PK4(p0, 0, pa0); PK4(p0, 8, pa1); PK4(p1, 0, pa2); PK4(p1, 8, pa3);
;     ...
; }
; __device__ __forceinline__ void qkt(f32x16& p0, f32x16& p1, const bf16* Ks, const bf16x8* qr, int r32, int hi) {
;   p0 = f32x16{}; p1 = f32x16{};
; #pragma unroll
;   for (int d0 = 0; d0 < 8; ++d0) { int cb = (d0 * 16 + hi * 8) * 2;
;     bf16x8 b0 = *reinterpret_cast<const bf16x8*>((const char*)Ks + KSWZ(r32, cb));
;     bf16x8 b1 = *reinterpret_cast<const bf16x8*>((const char*)Ks + KSWZ(32 + r32, cb));
;     p0 = __builtin_amdgcn_mfma_f32_32x32x16_bf16(b0, qr[d0], p0, 0, 0, 0);
;     p1 = __builtin_amdgcn_mfma_f32_32x32x16_bf16(b1, qr[d0], p1, 0, 0, 0); }
; }
; __device__ __forceinline__ int v_st(int k, int c) { const int kk = (k & ~0xC) | ((k & 4) << 1) | ((k & 8) >> 1); return ((kk >> 3) * 4 + (c >> 5)) * 512 + ((kk & 7) * 32 + (c & 31)) * 2; }
; __device__ __forceinline__ int v_rd_base(int lane) { return ((lane & 3) << 3) | (((lane >> 2) & 3) << 6) | (((lane >> 4) & 1) << 5) | (((lane >> 5) & 1) << 8); }
; template <int OFF> __device__ __forceinline__ s16x4 tr_read(int vb) {
;   s16x4 r; asm volatile("ds_read_b64_tr_b16 %0, %1 offset:%2" : "=&v"(r) : "v"(vb), "i"(OFF) : "memory"); return r;
; }
; template <int D0> __device__ __forceinline__ void pv_one(f32x16& od, int vb, bf16x8 pa0, bf16x8 pa1, bf16x8 pa2, bf16x8 pa3) {
;   const s16x4 l0 = tr_read<v_rd_off(D0, 0, 0)>(vb), h0 = tr_read<v_rd_off(D0, 0, 1)>(vb), l1 = tr_read<v_rd_off(D0, 1, 0)>(vb), h1 = tr_read<v_rd_off(D0, 1, 1)>(vb);
	v_mfma_f32_16x16x32_bf16 v[8:11], v[208:211], v[184:187], v[8:11]
	v_exp_f32_e32 v68, v68
	v_mfma_f32_16x16x32_bf16 v[40:43], v[208:211], v[192:195], v[40:43]
	ds_read_b64_tr_b16 v[200:201], v176 offset:57344
	ds_read_b64_tr_b16 v[202:203], v176 offset:61440
	v_exp_f32_e32 v69, v69
	v_mfma_f32_16x16x32_bf16 v[12:15], v[212:215], v[184:187], v[12:15]
	v_exp_f32_e32 v70, v70
	v_mfma_f32_16x16x32_bf16 v[44:47], v[212:215], v[192:195], v[44:47]
	ds_read_b64_tr_b16 v[204:205], v177 offset:57344
	ds_read_b64_tr_b16 v[206:207], v177 offset:61440
	v_exp_f32_e32 v71, v71
	s_waitcnt lgkmcnt(8)
	v_mfma_f32_16x16x32_bf16 v[16:19], v[230:233], v[184:187], v[16:19]
	v_exp_f32_e32 v72, v72
	v_mfma_f32_16x16x32_bf16 v[48:51], v[230:233], v[192:195], v[48:51]
	ds_read_b64_tr_b16 v[208:209], v178 offset:57344
	ds_read_b64_tr_b16 v[210:211], v178 offset:61440
	v_exp_f32_e32 v73, v73
	v_mfma_f32_16x16x32_bf16 v[20:23], v[234:237], v[184:187], v[20:23]
	v_exp_f32_e32 v74, v74
	v_mfma_f32_16x16x32_bf16 v[52:55], v[234:237], v[192:195], v[52:55]
	ds_read_b64_tr_b16 v[212:213], v179 offset:57344
	ds_read_b64_tr_b16 v[214:215], v179 offset:61440
	v_exp_f32_e32 v75, v75
	s_waitcnt lgkmcnt(8)
	v_mfma_f32_16x16x32_bf16 v[24:27], v[238:241], v[184:187], v[24:27]
	v_exp_f32_e32 v76, v76
	v_mfma_f32_16x16x32_bf16 v[56:59], v[238:241], v[192:195], v[56:59]
	ds_read_b64_tr_b16 v[230:231], v180 offset:57344
	ds_read_b64_tr_b16 v[232:233], v180 offset:61440
	v_exp_f32_e32 v77, v77
	v_mfma_f32_16x16x32_bf16 v[28:31], v[242:245], v[184:187], v[28:31]
	v_exp_f32_e32 v78, v78
	v_mfma_f32_16x16x32_bf16 v[60:63], v[242:245], v[192:195], v[60:63]
	ds_read_b64_tr_b16 v[234:235], v182 offset:57344
	ds_read_b64_tr_b16 v[236:237], v182 offset:61440
	v_exp_f32_e32 v79, v79
	s_waitcnt lgkmcnt(8)
	v_mfma_f32_16x16x32_bf16 v[0:3], v[200:203], v[188:191], v[0:3]
	v_exp_f32_e32 v80, v80
	v_mfma_f32_16x16x32_bf16 v[32:35], v[200:203], v[196:199], v[32:35]
	ds_read_b64_tr_b16 v[238:239], v216 offset:57344
	ds_read_b64_tr_b16 v[240:241], v216 offset:61440
	ds_read_b128 v[200:203], v172 offset:16384
	v_exp_f32_e32 v81, v81
	v_mfma_f32_16x16x32_bf16 v[4:7], v[204:207], v[188:191], v[4:7]
	v_exp_f32_e32 v82, v82
	v_mfma_f32_16x16x32_bf16 v[36:39], v[204:207], v[196:199], v[36:39]
	ds_read_b64_tr_b16 v[242:243], v217 offset:57344
	ds_read_b64_tr_b16 v[244:245], v217 offset:61440
	ds_read_b128 v[204:207], v172 offset:20480
	v_exp_f32_e32 v83, v83
	s_waitcnt lgkmcnt(10)
	v_mfma_f32_16x16x32_bf16 v[8:11], v[208:211], v[188:191], v[8:11]
	v_exp_f32_e32 v84, v84
	v_mfma_f32_16x16x32_bf16 v[40:43], v[208:211], v[196:199], v[40:43]
	ds_read_b128 v[208:211], v172 offset:24576
	v_exp_f32_e32 v85, v85
	v_mfma_f32_16x16x32_bf16 v[12:15], v[212:215], v[188:191], v[12:15]
	v_exp_f32_e32 v86, v86
	v_mfma_f32_16x16x32_bf16 v[44:47], v[212:215], v[196:199], v[44:47]
	ds_read_b128 v[212:215], v172 offset:28672
	v_exp_f32_e32 v87, v87
	s_waitcnt lgkmcnt(8)
	v_mfma_f32_16x16x32_bf16 v[16:19], v[230:233], v[188:191], v[16:19]
	v_exp_f32_e32 v88, v88
	v_mfma_f32_16x16x32_bf16 v[48:51], v[230:233], v[196:199], v[48:51]
	ds_read_b128 v[230:233], v173 offset:16384
	v_exp_f32_e32 v89, v89
	v_mfma_f32_16x16x32_bf16 v[20:23], v[234:237], v[188:191], v[20:23]
	v_exp_f32_e32 v90, v90
	v_mfma_f32_16x16x32_bf16 v[52:55], v[234:237], v[196:199], v[52:55]
	ds_read_b128 v[234:237], v173 offset:20480
	v_exp_f32_e32 v91, v91
	s_waitcnt lgkmcnt(5)
	v_mfma_f32_16x16x32_bf16 v[24:27], v[238:241], v[188:191], v[24:27]
	v_exp_f32_e32 v92, v92
	v_mfma_f32_16x16x32_bf16 v[56:59], v[238:241], v[196:199], v[56:59]
	ds_read_b128 v[238:241], v173 offset:24576
	v_exp_f32_e32 v93, v93
	v_mfma_f32_16x16x32_bf16 v[28:31], v[242:245], v[188:191], v[28:31]
	v_exp_f32_e32 v94, v94
	v_mfma_f32_16x16x32_bf16 v[60:63], v[242:245], v[196:199], v[60:63]
	ds_read_b128 v[242:245], v173 offset:28672
	v_exp_f32_e32 v95, v95
	s_waitcnt vmcnt(4)
	s_barrier
	s_add_i32 s44, s44, 1
	s_cmp_lt_u32 s44, 63
	s_cbranch_scc1 .Ldense_loop
	s_waitcnt lgkmcnt(6)
	v_mfma_f32_16x16x32_bf16 v[128:131], v[200:203], v[96:99], 0
	v_add_f32_e32 v169, v169, v64
	s_add_i32 m0, s32, 0x18000
	v_mfma_f32_16x16x32_bf16 v[132:135], v[200:203], v[112:115], 0
	ds_read_b128 v[200:203], v174 offset:16384
	v_add_f32_e32 v169, v169, v65
	v_cvt_pk_bf16_f32 v184, v64, v65
	global_load_lds_dwordx4 v181, s[0:1]
	v_mfma_f32_16x16x32_bf16 v[136:139], v[204:207], v[96:99], 0
	v_add_f32_e32 v169, v169, v66
	v_mfma_f32_16x16x32_bf16 v[140:143], v[204:207], v[112:115], 0
	ds_read_b128 v[204:207], v174 offset:20480
	v_add_f32_e32 v169, v169, v67
	v_cvt_pk_bf16_f32 v185, v66, v67
	s_waitcnt lgkmcnt(6)
	v_mfma_f32_16x16x32_bf16 v[144:147], v[208:211], v[96:99], 0
	v_add_f32_e32 v222, v222, v68
	s_add_i32 m0, s32, 0x1a000
	v_mfma_f32_16x16x32_bf16 v[148:151], v[208:211], v[112:115], 0
	ds_read_b128 v[208:211], v174 offset:24576
	v_add_f32_e32 v222, v222, v69
	v_cvt_pk_bf16_f32 v186, v72, v73
	global_load_lds_dwordx4 v247, s[0:1]
	s_add_u32 s0, s0, 0x150000
	s_addc_u32 s1, s1, 0
	v_mfma_f32_16x16x32_bf16 v[152:155], v[212:215], v[96:99], 0
	v_add_f32_e32 v222, v222, v70
	v_mfma_f32_16x16x32_bf16 v[156:159], v[212:215], v[112:115], 0
	ds_read_b128 v[212:215], v174 offset:28672
	v_add_f32_e32 v222, v222, v71
	v_cvt_pk_bf16_f32 v187, v74, v75
	s_waitcnt lgkmcnt(6)
	v_mfma_f32_16x16x32_bf16 v[128:131], v[230:233], v[100:103], v[128:131]
	v_add_f32_e32 v169, v169, v72
	v_mfma_f32_16x16x32_bf16 v[132:135], v[230:233], v[116:119], v[132:135]
	ds_read_b128 v[230:233], v175 offset:16384
	v_add_f32_e32 v169, v169, v73
	v_cvt_pk_bf16_f32 v188, v80, v81
	v_mfma_f32_16x16x32_bf16 v[136:139], v[234:237], v[100:103], v[136:139]
	v_add_f32_e32 v169, v169, v74
	v_mfma_f32_16x16x32_bf16 v[140:143], v[234:237], v[116:119], v[140:143]
	ds_read_b128 v[234:237], v175 offset:20480
	v_add_f32_e32 v169, v169, v75
	v_cvt_pk_bf16_f32 v189, v82, v83
	s_waitcnt lgkmcnt(6)
; __device__ __forceinline__ void partialSM(f32x16& p0, f32x16& p1, float& m_reg, float& mn, float& alpha) {
;     ...
;   for (int r = 0; r < 16; ++r) p0[r] = __builtin_amdgcn_exp2f(p0[r]);
; }
; __device__ __forceinline__ void finishSM(f32x16& p0, f32x16& p1, float alpha, float& l_reg, bf16x8& pa0, bf16x8& pa1, bf16x8& pa2, bf16x8& pa3) {
; #pragma unroll
;   for (int r = 0; r < 16; ++r) p1[r] = __builtin_amdgcn_exp2f(p1[r]);
;   float ps = 0;
; #pragma unroll
;   for (int r = 0; r < 16; ++r) ps += p0[r];
; #pragma unroll
;   for (int r = 0; r < 16; ++r) ps += p1[r];
;   { auto rr = __builtin_amdgcn_permlane32_swap(__float_as_uint(ps), __float_as_uint(ps), false, false);
;     ps = __uint_as_float(rr[0]) + __uint_as_float(rr[1]); }
;   l_reg = l_reg * alpha + ps;
;     ...
;   PK4(p0, 0, pa0); PK4(p0, 8, pa1); PK4(p1, 0, pa2); PK4(p1, 8, pa3);
;     ...
; }
; __device__ __forceinline__ void qkt(f32x16& p0, f32x16& p1, const bf16* Ks, const bf16x8* qr, int r32, int hi) {
;   p0 = f32x16{}; p1 = f32x16{};
; #pragma unroll
;   for (int d0 = 0; d0 < 8; ++d0) { int cb = (d0 * 16 + hi * 8) * 2;
;     bf16x8 b0 = *reinterpret_cast<const bf16x8*>((const char*)Ks + KSWZ(r32, cb));
;     bf16x8 b1 = *reinterpret_cast<const bf16x8*>((const char*)Ks + KSWZ(32 + r32, cb));
;     p0 = __builtin_amdgcn_mfma_f32_32x32x16_bf16(b0, qr[d0], p0, 0, 0, 0);
;     p1 = __builtin_amdgcn_mfma_f32_32x32x16_bf16(b1, qr[d0], p1, 0, 0, 0); }
; }
; __device__ __forceinline__ int v_st(int k, int c) { const int kk = (k & ~0xC) | ((k & 4) << 1) | ((k & 8) >> 1); return ((kk >> 3) * 4 + (c >> 5)) * 512 + ((kk & 7) * 32 + (c & 31)) * 2; }
; __device__ __forceinline__ int v_rd_base(int lane) { return ((lane & 3) << 3) | (((lane >> 2) & 3) << 6) | (((lane >> 4) & 1) << 5) | (((lane >> 5) & 1) << 8); }
; template <int OFF> __device__ __forceinline__ s16x4 tr_read(int vb) {
;   s16x4 r; asm volatile("ds_read_b64_tr_b16 %0, %1 offset:%2" : "=&v"(r) : "v"(vb), "i"(OFF) : "memory"); return r;
; }
; template <int D0> __device__ __forceinline__ void pv_one(f32x16& od, int vb, bf16x8 pa0, bf16x8 pa1, bf16x8 pa2, bf16x8 pa3) {
;   const s16x4 l0 = tr_read<v_rd_off(D0, 0, 0)>(vb), h0 = tr_read<v_rd_off(D0, 0, 1)>(vb), l1 = tr_read<v_rd_off(D0, 1, 0)>(vb), h1 = tr_read<v_rd_off(D0, 1, 1)>(vb);
	v_mfma_f32_16x16x32_bf16 v[144:147], v[238:241], v[100:103], v[144:147]
	v_add_f32_e32 v222, v222, v76
	v_mfma_f32_16x16x32_bf16 v[148:151], v[238:241], v[116:119], v[148:151]
	ds_read_b128 v[238:241], v175 offset:24576
	v_add_f32_e32 v222, v222, v77
	v_cvt_pk_bf16_f32 v190, v88, v89
	v_mfma_f32_16x16x32_bf16 v[152:155], v[242:245], v[100:103], v[152:155]
	v_add_f32_e32 v222, v222, v78
	v_mfma_f32_16x16x32_bf16 v[156:159], v[242:245], v[116:119], v[156:159]
	ds_read_b128 v[242:245], v175 offset:28672
	v_add_f32_e32 v222, v222, v79
	v_cvt_pk_bf16_f32 v191, v90, v91
	s_waitcnt lgkmcnt(6)
	v_mfma_f32_16x16x32_bf16 v[128:131], v[200:203], v[104:107], v[128:131]
	v_add_f32_e32 v169, v169, v80
	v_mfma_f32_16x16x32_bf16 v[132:135], v[200:203], v[120:123], v[132:135]
	v_add_f32_e32 v169, v169, v81
	v_cvt_pk_bf16_f32 v192, v68, v69
	v_mfma_f32_16x16x32_bf16 v[136:139], v[204:207], v[104:107], v[136:139]
	v_add_f32_e32 v169, v169, v82
	v_mfma_f32_16x16x32_bf16 v[140:143], v[204:207], v[120:123], v[140:143]
	v_add_f32_e32 v169, v169, v83
	v_cvt_pk_bf16_f32 v193, v70, v71
	s_waitcnt lgkmcnt(4)
	v_mfma_f32_16x16x32_bf16 v[144:147], v[208:211], v[104:107], v[144:147]
	ds_read_b64_tr_b16 v[200:201], v176 offset:0
	ds_read_b64_tr_b16 v[202:203], v176 offset:4096
	v_add_f32_e32 v222, v222, v84
	v_mfma_f32_16x16x32_bf16 v[148:151], v[208:211], v[120:123], v[148:151]
	v_add_f32_e32 v222, v222, v85
	v_cvt_pk_bf16_f32 v194, v76, v77
	v_mfma_f32_16x16x32_bf16 v[152:155], v[212:215], v[104:107], v[152:155]
	ds_read_b64_tr_b16 v[204:205], v177 offset:0
	ds_read_b64_tr_b16 v[206:207], v177 offset:4096
	v_add_f32_e32 v222, v222, v86
	v_mfma_f32_16x16x32_bf16 v[156:159], v[212:215], v[120:123], v[156:159]
	v_add_f32_e32 v222, v222, v87
	v_cvt_pk_bf16_f32 v195, v78, v79
	s_waitcnt lgkmcnt(6)
	v_mfma_f32_16x16x32_bf16 v[128:131], v[230:233], v[108:111], v[128:131]
	ds_read_b64_tr_b16 v[208:209], v178 offset:0
	ds_read_b64_tr_b16 v[210:211], v178 offset:4096
	v_add_f32_e32 v169, v169, v88
	v_mfma_f32_16x16x32_bf16 v[132:135], v[230:233], v[124:127], v[132:135]
	v_add_f32_e32 v169, v169, v89
	v_cvt_pk_bf16_f32 v196, v84, v85
	v_mfma_f32_16x16x32_bf16 v[136:139], v[234:237], v[108:111], v[136:139]
	ds_read_b64_tr_b16 v[212:213], v179 offset:0
	ds_read_b64_tr_b16 v[214:215], v179 offset:4096
	v_add_f32_e32 v169, v169, v90
	v_mfma_f32_16x16x32_bf16 v[140:143], v[234:237], v[124:127], v[140:143]
	v_add_f32_e32 v169, v169, v91
	v_cvt_pk_bf16_f32 v197, v86, v87
	s_waitcnt lgkmcnt(8)
	v_mfma_f32_16x16x32_bf16 v[144:147], v[238:241], v[108:111], v[144:147]
	ds_read_b64_tr_b16 v[230:231], v180 offset:0
	ds_read_b64_tr_b16 v[232:233], v180 offset:4096
	v_add_f32_e32 v222, v222, v92
	v_mfma_f32_16x16x32_bf16 v[148:151], v[238:241], v[124:127], v[148:151]
	v_add_f32_e32 v222, v222, v93
	v_cvt_pk_bf16_f32 v198, v92, v93
	v_mfma_f32_16x16x32_bf16 v[152:155], v[242:245], v[108:111], v[152:155]
	ds_read_b64_tr_b16 v[234:235], v182 offset:0
	ds_read_b64_tr_b16 v[236:237], v182 offset:4096
	v_add_f32_e32 v222, v222, v94
	v_mfma_f32_16x16x32_bf16 v[156:159], v[242:245], v[124:127], v[156:159]
	v_add_f32_e32 v222, v222, v95
	v_cvt_pk_bf16_f32 v199, v94, v95
	s_waitcnt lgkmcnt(8)
	v_mfma_f32_16x16x32_bf16 v[0:3], v[200:203], v[184:187], v[0:3]
	v_exp_f32_e32 v128, v128
	v_mfma_f32_16x16x32_bf16 v[32:35], v[200:203], v[192:195], v[32:35]
	ds_read_b64_tr_b16 v[238:239], v216 offset:0
	ds_read_b64_tr_b16 v[240:241], v216 offset:4096
	v_exp_f32_e32 v129, v129
	v_mfma_f32_16x16x32_bf16 v[4:7], v[204:207], v[184:187], v[4:7]
	v_exp_f32_e32 v130, v130
	v_mfma_f32_16x16x32_bf16 v[36:39], v[204:207], v[192:195], v[36:39]
	ds_read_b64_tr_b16 v[242:243], v217 offset:0
	ds_read_b64_tr_b16 v[244:245], v217 offset:4096
	v_exp_f32_e32 v131, v131
	s_waitcnt lgkmcnt(8)
	v_mfma_f32_16x16x32_bf16 v[8:11], v[208:211], v[184:187], v[8:11]
	v_exp_f32_e32 v132, v132
	v_mfma_f32_16x16x32_bf16 v[40:43], v[208:211], v[192:195], v[40:43]
	ds_read_b64_tr_b16 v[200:201], v176 offset:8192
	ds_read_b64_tr_b16 v[202:203], v176 offset:12288
	v_exp_f32_e32 v133, v133
	v_mfma_f32_16x16x32_bf16 v[12:15], v[212:215], v[184:187], v[12:15]
	v_exp_f32_e32 v134, v134
	v_mfma_f32_16x16x32_bf16 v[44:47], v[212:215], v[192:195], v[44:47]
	ds_read_b64_tr_b16 v[204:205], v177 offset:8192
	ds_read_b64_tr_b16 v[206:207], v177 offset:12288
	v_exp_f32_e32 v135, v135
	s_waitcnt lgkmcnt(8)
	v_mfma_f32_16x16x32_bf16 v[16:19], v[230:233], v[184:187], v[16:19]
	v_exp_f32_e32 v136, v136
	v_mfma_f32_16x16x32_bf16 v[48:51], v[230:233], v[192:195], v[48:51]
	ds_read_b64_tr_b16 v[208:209], v178 offset:8192
	ds_read_b64_tr_b16 v[210:211], v178 offset:12288
	v_exp_f32_e32 v137, v137
	v_mfma_f32_16x16x32_bf16 v[20:23], v[234:237], v[184:187], v[20:23]
	v_exp_f32_e32 v138, v138
	v_mfma_f32_16x16x32_bf16 v[52:55], v[234:237], v[192:195], v[52:55]
	ds_read_b64_tr_b16 v[212:213], v179 offset:8192
	ds_read_b64_tr_b16 v[214:215], v179 offset:12288
	v_exp_f32_e32 v139, v139
	s_waitcnt lgkmcnt(8)
	v_mfma_f32_16x16x32_bf16 v[24:27], v[238:241], v[184:187], v[24:27]
	v_exp_f32_e32 v140, v140
	v_mfma_f32_16x16x32_bf16 v[56:59], v[238:241], v[192:195], v[56:59]
	ds_read_b64_tr_b16 v[230:231], v180 offset:8192
	ds_read_b64_tr_b16 v[232:233], v180 offset:12288
	v_exp_f32_e32 v141, v141
	v_mfma_f32_16x16x32_bf16 v[28:31], v[242:245], v[184:187], v[28:31]
	v_exp_f32_e32 v142, v142
	v_mfma_f32_16x16x32_bf16 v[60:63], v[242:245], v[192:195], v[60:63]
	ds_read_b64_tr_b16 v[234:235], v182 offset:8192
	ds_read_b64_tr_b16 v[236:237], v182 offset:12288
	v_exp_f32_e32 v143, v143
	s_waitcnt lgkmcnt(8)
; __device__ __forceinline__ void partialSM(f32x16& p0, f32x16& p1, float& m_reg, float& mn, float& alpha) {
;     ...
;   for (int r = 0; r < 16; ++r) p0[r] = __builtin_amdgcn_exp2f(p0[r]);
; }
; __device__ __forceinline__ void finishSM(f32x16& p0, f32x16& p1, float alpha, float& l_reg, bf16x8& pa0, bf16x8& pa1, bf16x8& pa2, bf16x8& pa3) {
; #pragma unroll
;   for (int r = 0; r < 16; ++r) p1[r] = __builtin_amdgcn_exp2f(p1[r]);
;   float ps = 0;
; #pragma unroll
;   for (int r = 0; r < 16; ++r) ps += p0[r];
; #pragma unroll
;   for (int r = 0; r < 16; ++r) ps += p1[r];
;   { auto rr = __builtin_amdgcn_permlane32_swap(__float_as_uint(ps), __float_as_uint(ps), false, false);
;     ps = __uint_as_float(rr[0]) + __uint_as_float(rr[1]); }
;   l_reg = l_reg * alpha + ps;
;     ...
;   PK4(p0, 0, pa0); PK4(p0, 8, pa1); PK4(p1, 0, pa2); PK4(p1, 8, pa3);
;     ...
; }
; __device__ __forceinline__ void qkt(f32x16& p0, f32x16& p1, const bf16* Ks, const bf16x8* qr, int r32, int hi) {
;   p0 = f32x16{}; p1 = f32x16{};
; #pragma unroll
;   for (int d0 = 0; d0 < 8; ++d0) { int cb = (d0 * 16 + hi * 8) * 2;
;     bf16x8 b0 = *reinterpret_cast<const bf16x8*>((const char*)Ks + KSWZ(r32, cb));
;     bf16x8 b1 = *reinterpret_cast<const bf16x8*>((const char*)Ks + KSWZ(32 + r32, cb));
;     p0 = __builtin_amdgcn_mfma_f32_32x32x16_bf16(b0, qr[d0], p0, 0, 0, 0);
;     p1 = __builtin_amdgcn_mfma_f32_32x32x16_bf16(b1, qr[d0], p1, 0, 0, 0); }
; }
; __device__ __forceinline__ int v_st(int k, int c) { const int kk = (k & ~0xC) | ((k & 4) << 1) | ((k & 8) >> 1); return ((kk >> 3) * 4 + (c >> 5)) * 512 + ((kk & 7) * 32 + (c & 31)) * 2; }
; __device__ __forceinline__ int v_rd_base(int lane) { return ((lane & 3) << 3) | (((lane >> 2) & 3) << 6) | (((lane >> 4) & 1) << 5) | (((lane >> 5) & 1) << 8); }
; template <int OFF> __device__ __forceinline__ s16x4 tr_read(int vb) {
;   s16x4 r; asm volatile("ds_read_b64_tr_b16 %0, %1 offset:%2" : "=&v"(r) : "v"(vb), "i"(OFF) : "memory"); return r;
; }
; template <int D0> __device__ __forceinline__ void pv_one(f32x16& od, int vb, bf16x8 pa0, bf16x8 pa1, bf16x8 pa2, bf16x8 pa3) {
;   const s16x4 l0 = tr_read<v_rd_off(D0, 0, 0)>(vb), h0 = tr_read<v_rd_off(D0, 0, 1)>(vb), l1 = tr_read<v_rd_off(D0, 1, 0)>(vb), h1 = tr_read<v_rd_off(D0, 1, 1)>(vb);
	v_mfma_f32_16x16x32_bf16 v[0:3], v[200:203], v[188:191], v[0:3]
	v_exp_f32_e32 v144, v144
	v_mfma_f32_16x16x32_bf16 v[32:35], v[200:203], v[196:199], v[32:35]
	ds_read_b64_tr_b16 v[238:239], v216 offset:8192
	ds_read_b64_tr_b16 v[240:241], v216 offset:12288
	ds_read_b128 v[200:203], v172 offset:32768
	v_exp_f32_e32 v145, v145
	v_mfma_f32_16x16x32_bf16 v[4:7], v[204:207], v[188:191], v[4:7]
	v_exp_f32_e32 v146, v146
	v_mfma_f32_16x16x32_bf16 v[36:39], v[204:207], v[196:199], v[36:39]
	ds_read_b64_tr_b16 v[242:243], v217 offset:8192
	ds_read_b64_tr_b16 v[244:245], v217 offset:12288
	ds_read_b128 v[204:207], v172 offset:36864
	v_exp_f32_e32 v147, v147
	s_waitcnt lgkmcnt(10)
	v_mfma_f32_16x16x32_bf16 v[8:11], v[208:211], v[188:191], v[8:11]
	v_exp_f32_e32 v148, v148
	v_mfma_f32_16x16x32_bf16 v[40:43], v[208:211], v[196:199], v[40:43]
	ds_read_b128 v[208:211], v172 offset:40960
	v_exp_f32_e32 v149, v149
	v_mfma_f32_16x16x32_bf16 v[12:15], v[212:215], v[188:191], v[12:15]
	v_exp_f32_e32 v150, v150
	v_mfma_f32_16x16x32_bf16 v[44:47], v[212:215], v[196:199], v[44:47]
	ds_read_b128 v[212:215], v172 offset:45056
	v_exp_f32_e32 v151, v151
	s_waitcnt lgkmcnt(8)
	v_mfma_f32_16x16x32_bf16 v[16:19], v[230:233], v[188:191], v[16:19]
	v_exp_f32_e32 v152, v152
	v_mfma_f32_16x16x32_bf16 v[48:51], v[230:233], v[196:199], v[48:51]
	ds_read_b128 v[230:233], v173 offset:32768
	v_exp_f32_e32 v153, v153
	v_mfma_f32_16x16x32_bf16 v[20:23], v[234:237], v[188:191], v[20:23]
	v_exp_f32_e32 v154, v154
	v_mfma_f32_16x16x32_bf16 v[52:55], v[234:237], v[196:199], v[52:55]
	ds_read_b128 v[234:237], v173 offset:36864
	v_exp_f32_e32 v155, v155
	s_waitcnt lgkmcnt(5)
	v_mfma_f32_16x16x32_bf16 v[24:27], v[238:241], v[188:191], v[24:27]
	v_exp_f32_e32 v156, v156
	v_mfma_f32_16x16x32_bf16 v[56:59], v[238:241], v[196:199], v[56:59]
	ds_read_b128 v[238:241], v173 offset:40960
	v_exp_f32_e32 v157, v157
	v_mfma_f32_16x16x32_bf16 v[28:31], v[242:245], v[188:191], v[28:31]
	v_exp_f32_e32 v158, v158
	v_mfma_f32_16x16x32_bf16 v[60:63], v[242:245], v[196:199], v[60:63]
	ds_read_b128 v[242:245], v173 offset:45056
	v_exp_f32_e32 v159, v159
	s_waitcnt vmcnt(2)
	s_barrier
	s_waitcnt lgkmcnt(6)
	v_mfma_f32_16x16x32_bf16 v[64:67], v[200:203], v[96:99], 0
	v_add_f32_e32 v169, v169, v128
	s_add_i32 m0, s32, 0x1c000
	v_mfma_f32_16x16x32_bf16 v[68:71], v[200:203], v[112:115], 0
	ds_read_b128 v[200:203], v174 offset:32768
	v_add_f32_e32 v169, v169, v129
	v_cvt_pk_bf16_f32 v184, v128, v129
	global_load_lds_dwordx4 v181, s[0:1]
	v_mfma_f32_16x16x32_bf16 v[72:75], v[204:207], v[96:99], 0
	v_add_f32_e32 v169, v169, v130
	v_mfma_f32_16x16x32_bf16 v[76:79], v[204:207], v[112:115], 0
	ds_read_b128 v[204:207], v174 offset:36864
	v_add_f32_e32 v169, v169, v131
	v_cvt_pk_bf16_f32 v185, v130, v131
	s_waitcnt lgkmcnt(6)
	v_mfma_f32_16x16x32_bf16 v[80:83], v[208:211], v[96:99], 0
	v_add_f32_e32 v222, v222, v132
	s_add_i32 m0, s32, 0x1e000
	v_mfma_f32_16x16x32_bf16 v[84:87], v[208:211], v[112:115], 0
	ds_read_b128 v[208:211], v174 offset:40960
	v_add_f32_e32 v222, v222, v133
	v_cvt_pk_bf16_f32 v186, v136, v137
	global_load_lds_dwordx4 v247, s[0:1]
	s_add_u32 s0, s0, 0x150000
	s_addc_u32 s1, s1, 0
	v_mfma_f32_16x16x32_bf16 v[88:91], v[212:215], v[96:99], 0
	v_add_f32_e32 v222, v222, v134
	v_mfma_f32_16x16x32_bf16 v[92:95], v[212:215], v[112:115], 0
	ds_read_b128 v[212:215], v174 offset:45056
	v_add_f32_e32 v222, v222, v135
	v_cvt_pk_bf16_f32 v187, v138, v139
	s_waitcnt lgkmcnt(6)
	v_mfma_f32_16x16x32_bf16 v[64:67], v[230:233], v[100:103], v[64:67]
	v_add_f32_e32 v169, v169, v136
	v_mfma_f32_16x16x32_bf16 v[68:71], v[230:233], v[116:119], v[68:71]
	ds_read_b128 v[230:233], v175 offset:32768
	v_add_f32_e32 v169, v169, v137
	v_cvt_pk_bf16_f32 v188, v144, v145
	v_mfma_f32_16x16x32_bf16 v[72:75], v[234:237], v[100:103], v[72:75]
	v_add_f32_e32 v169, v169, v138
	v_mfma_f32_16x16x32_bf16 v[76:79], v[234:237], v[116:119], v[76:79]
	ds_read_b128 v[234:237], v175 offset:36864
	v_add_f32_e32 v169, v169, v139
	v_cvt_pk_bf16_f32 v189, v146, v147
	s_waitcnt lgkmcnt(6)
	v_mfma_f32_16x16x32_bf16 v[80:83], v[238:241], v[100:103], v[80:83]
	v_add_f32_e32 v222, v222, v140
	v_mfma_f32_16x16x32_bf16 v[84:87], v[238:241], v[116:119], v[84:87]
	ds_read_b128 v[238:241], v175 offset:40960
	v_add_f32_e32 v222, v222, v141
	v_cvt_pk_bf16_f32 v190, v152, v153
	v_mfma_f32_16x16x32_bf16 v[88:91], v[242:245], v[100:103], v[88:91]
	v_add_f32_e32 v222, v222, v142
	v_mfma_f32_16x16x32_bf16 v[92:95], v[242:245], v[116:119], v[92:95]
	ds_read_b128 v[242:245], v175 offset:45056
	v_add_f32_e32 v222, v222, v143
	v_cvt_pk_bf16_f32 v191, v154, v155
	s_waitcnt lgkmcnt(6)
	v_mfma_f32_16x16x32_bf16 v[64:67], v[200:203], v[104:107], v[64:67]
	v_add_f32_e32 v169, v169, v144
	v_mfma_f32_16x16x32_bf16 v[68:71], v[200:203], v[120:123], v[68:71]
	v_add_f32_e32 v169, v169, v145
	v_cvt_pk_bf16_f32 v192, v132, v133
	v_mfma_f32_16x16x32_bf16 v[72:75], v[204:207], v[104:107], v[72:75]
	v_add_f32_e32 v169, v169, v146
	v_mfma_f32_16x16x32_bf16 v[76:79], v[204:207], v[120:123], v[76:79]
	v_add_f32_e32 v169, v169, v147
	v_cvt_pk_bf16_f32 v193, v134, v135
	s_waitcnt lgkmcnt(4)
	v_mfma_f32_16x16x32_bf16 v[80:83], v[208:211], v[104:107], v[80:83]
	ds_read_b64_tr_b16 v[200:201], v176 offset:16384
	ds_read_b64_tr_b16 v[202:203], v176 offset:20480
	v_add_f32_e32 v222, v222, v148
	v_mfma_f32_16x16x32_bf16 v[84:87], v[208:211], v[120:123], v[84:87]
	v_add_f32_e32 v222, v222, v149
	v_cvt_pk_bf16_f32 v194, v140, v141
	v_mfma_f32_16x16x32_bf16 v[88:91], v[212:215], v[104:107], v[88:91]
	ds_read_b64_tr_b16 v[204:205], v177 offset:16384
	ds_read_b64_tr_b16 v[206:207], v177 offset:20480
	v_add_f32_e32 v222, v222, v150
	v_mfma_f32_16x16x32_bf16 v[92:95], v[212:215], v[120:123], v[92:95]
	v_add_f32_e32 v222, v222, v151
	v_cvt_pk_bf16_f32 v195, v142, v143
	s_waitcnt lgkmcnt(6)
; __device__ __forceinline__ void partialSM(f32x16& p0, f32x16& p1, float& m_reg, float& mn, float& alpha) {
;     ...
;   for (int r = 0; r < 16; ++r) p0[r] = __builtin_amdgcn_exp2f(p0[r]);
; }
; __device__ __forceinline__ void finishSM(f32x16& p0, f32x16& p1, float alpha, float& l_reg, bf16x8& pa0, bf16x8& pa1, bf16x8& pa2, bf16x8& pa3) {
; #pragma unroll
;   for (int r = 0; r < 16; ++r) p1[r] = __builtin_amdgcn_exp2f(p1[r]);
;   float ps = 0;
; #pragma unroll
;   for (int r = 0; r < 16; ++r) ps += p0[r];
; #pragma unroll
;   for (int r = 0; r < 16; ++r) ps += p1[r];
;   { auto rr = __builtin_amdgcn_permlane32_swap(__float_as_uint(ps), __float_as_uint(ps), false, false);
;     ps = __uint_as_float(rr[0]) + __uint_as_float(rr[1]); }
;   l_reg = l_reg * alpha + ps;
;     ...
;   PK4(p0, 0, pa0); PK4(p0, 8, pa1); PK4(p1, 0, pa2); PK4(p1, 8, pa3);
;     ...
; }
; __device__ __forceinline__ void qkt(f32x16& p0, f32x16& p1, const bf16* Ks, const bf16x8* qr, int r32, int hi) {
;   p0 = f32x16{}; p1 = f32x16{};
; #pragma unroll
;   for (int d0 = 0; d0 < 8; ++d0) { int cb = (d0 * 16 + hi * 8) * 2;
;     bf16x8 b0 = *reinterpret_cast<const bf16x8*>((const char*)Ks + KSWZ(r32, cb));
;     bf16x8 b1 = *reinterpret_cast<const bf16x8*>((const char*)Ks + KSWZ(32 + r32, cb));
;     p0 = __builtin_amdgcn_mfma_f32_32x32x16_bf16(b0, qr[d0], p0, 0, 0, 0);
;     p1 = __builtin_amdgcn_mfma_f32_32x32x16_bf16(b1, qr[d0], p1, 0, 0, 0); }
; }
; __device__ __forceinline__ int v_st(int k, int c) { const int kk = (k & ~0xC) | ((k & 4) << 1) | ((k & 8) >> 1); return ((kk >> 3) * 4 + (c >> 5)) * 512 + ((kk & 7) * 32 + (c & 31)) * 2; }
; __device__ __forceinline__ int v_rd_base(int lane) { return ((lane & 3) << 3) | (((lane >> 2) & 3) << 6) | (((lane >> 4) & 1) << 5) | (((lane >> 5) & 1) << 8); }
; template <int OFF> __device__ __forceinline__ s16x4 tr_read(int vb) {
;   s16x4 r; asm volatile("ds_read_b64_tr_b16 %0, %1 offset:%2" : "=&v"(r) : "v"(vb), "i"(OFF) : "memory"); return r;
; }
; template <int D0> __device__ __forceinline__ void pv_one(f32x16& od, int vb, bf16x8 pa0, bf16x8 pa1, bf16x8 pa2, bf16x8 pa3) {
;   const s16x4 l0 = tr_read<v_rd_off(D0, 0, 0)>(vb), h0 = tr_read<v_rd_off(D0, 0, 1)>(vb), l1 = tr_read<v_rd_off(D0, 1, 0)>(vb), h1 = tr_read<v_rd_off(D0, 1, 1)>(vb);
	v_mfma_f32_16x16x32_bf16 v[64:67], v[230:233], v[108:111], v[64:67]
	ds_read_b64_tr_b16 v[208:209], v178 offset:16384
	ds_read_b64_tr_b16 v[210:211], v178 offset:20480
	v_add_f32_e32 v169, v169, v152
	v_mfma_f32_16x16x32_bf16 v[68:71], v[230:233], v[124:127], v[68:71]
	v_add_f32_e32 v169, v169, v153
	v_cvt_pk_bf16_f32 v196, v148, v149
	v_mfma_f32_16x16x32_bf16 v[72:75], v[234:237], v[108:111], v[72:75]
	ds_read_b64_tr_b16 v[212:213], v179 offset:16384
	ds_read_b64_tr_b16 v[214:215], v179 offset:20480
	v_add_f32_e32 v169, v169, v154
	v_mfma_f32_16x16x32_bf16 v[76:79], v[234:237], v[124:127], v[76:79]
	v_add_f32_e32 v169, v169, v155
	v_cvt_pk_bf16_f32 v197, v150, v151
	s_waitcnt lgkmcnt(8)
	v_mfma_f32_16x16x32_bf16 v[80:83], v[238:241], v[108:111], v[80:83]
	ds_read_b64_tr_b16 v[230:231], v180 offset:16384
	ds_read_b64_tr_b16 v[232:233], v180 offset:20480
	v_add_f32_e32 v222, v222, v156
	v_mfma_f32_16x16x32_bf16 v[84:87], v[238:241], v[124:127], v[84:87]
	v_add_f32_e32 v222, v222, v157
	v_cvt_pk_bf16_f32 v198, v156, v157
	v_mfma_f32_16x16x32_bf16 v[88:91], v[242:245], v[108:111], v[88:91]
	ds_read_b64_tr_b16 v[234:235], v182 offset:16384
	ds_read_b64_tr_b16 v[236:237], v182 offset:20480
	v_add_f32_e32 v222, v222, v158
	v_mfma_f32_16x16x32_bf16 v[92:95], v[242:245], v[124:127], v[92:95]
	v_add_f32_e32 v222, v222, v159
	v_cvt_pk_bf16_f32 v199, v158, v159
	s_waitcnt lgkmcnt(8)
	v_mfma_f32_16x16x32_bf16 v[0:3], v[200:203], v[184:187], v[0:3]
	v_exp_f32_e32 v64, v64
	v_mfma_f32_16x16x32_bf16 v[32:35], v[200:203], v[192:195], v[32:35]
	ds_read_b64_tr_b16 v[238:239], v216 offset:16384
	ds_read_b64_tr_b16 v[240:241], v216 offset:20480
	v_exp_f32_e32 v65, v65
	v_mfma_f32_16x16x32_bf16 v[4:7], v[204:207], v[184:187], v[4:7]
	v_exp_f32_e32 v66, v66
	v_mfma_f32_16x16x32_bf16 v[36:39], v[204:207], v[192:195], v[36:39]
	ds_read_b64_tr_b16 v[242:243], v217 offset:16384
	ds_read_b64_tr_b16 v[244:245], v217 offset:20480
	v_exp_f32_e32 v67, v67
	s_waitcnt lgkmcnt(8)
	v_mfma_f32_16x16x32_bf16 v[8:11], v[208:211], v[184:187], v[8:11]
	v_exp_f32_e32 v68, v68
	v_mfma_f32_16x16x32_bf16 v[40:43], v[208:211], v[192:195], v[40:43]
	ds_read_b64_tr_b16 v[200:201], v176 offset:24576
	ds_read_b64_tr_b16 v[202:203], v176 offset:28672
	v_exp_f32_e32 v69, v69
	v_mfma_f32_16x16x32_bf16 v[12:15], v[212:215], v[184:187], v[12:15]
	v_exp_f32_e32 v70, v70
	v_mfma_f32_16x16x32_bf16 v[44:47], v[212:215], v[192:195], v[44:47]
	ds_read_b64_tr_b16 v[204:205], v177 offset:24576
	ds_read_b64_tr_b16 v[206:207], v177 offset:28672
	v_exp_f32_e32 v71, v71
	s_waitcnt lgkmcnt(8)
	v_mfma_f32_16x16x32_bf16 v[16:19], v[230:233], v[184:187], v[16:19]
	v_exp_f32_e32 v72, v72
	v_mfma_f32_16x16x32_bf16 v[48:51], v[230:233], v[192:195], v[48:51]
	ds_read_b64_tr_b16 v[208:209], v178 offset:24576
	ds_read_b64_tr_b16 v[210:211], v178 offset:28672
	v_exp_f32_e32 v73, v73
	v_mfma_f32_16x16x32_bf16 v[20:23], v[234:237], v[184:187], v[20:23]
	v_exp_f32_e32 v74, v74
	v_mfma_f32_16x16x32_bf16 v[52:55], v[234:237], v[192:195], v[52:55]
	ds_read_b64_tr_b16 v[212:213], v179 offset:24576
	ds_read_b64_tr_b16 v[214:215], v179 offset:28672
	v_exp_f32_e32 v75, v75
	s_waitcnt lgkmcnt(8)
	v_mfma_f32_16x16x32_bf16 v[24:27], v[238:241], v[184:187], v[24:27]
	v_exp_f32_e32 v76, v76
	v_mfma_f32_16x16x32_bf16 v[56:59], v[238:241], v[192:195], v[56:59]
	ds_read_b64_tr_b16 v[230:231], v180 offset:24576
	ds_read_b64_tr_b16 v[232:233], v180 offset:28672
	v_exp_f32_e32 v77, v77
	v_mfma_f32_16x16x32_bf16 v[28:31], v[242:245], v[184:187], v[28:31]
	v_exp_f32_e32 v78, v78
	v_mfma_f32_16x16x32_bf16 v[60:63], v[242:245], v[192:195], v[60:63]
	ds_read_b64_tr_b16 v[234:235], v182 offset:24576
	ds_read_b64_tr_b16 v[236:237], v182 offset:28672
	v_exp_f32_e32 v79, v79
	s_waitcnt lgkmcnt(8)
	v_mfma_f32_16x16x32_bf16 v[0:3], v[200:203], v[188:191], v[0:3]
	v_exp_f32_e32 v80, v80
	v_mfma_f32_16x16x32_bf16 v[32:35], v[200:203], v[196:199], v[32:35]
	ds_read_b64_tr_b16 v[238:239], v216 offset:24576
	ds_read_b64_tr_b16 v[240:241], v216 offset:28672
	ds_read_b128 v[200:203], v172 offset:49152
	v_exp_f32_e32 v81, v81
	v_mfma_f32_16x16x32_bf16 v[4:7], v[204:207], v[188:191], v[4:7]
	v_exp_f32_e32 v82, v82
	v_mfma_f32_16x16x32_bf16 v[36:39], v[204:207], v[196:199], v[36:39]
	ds_read_b64_tr_b16 v[242:243], v217 offset:24576
	ds_read_b64_tr_b16 v[244:245], v217 offset:28672
	ds_read_b128 v[204:207], v172 offset:53248
	v_exp_f32_e32 v83, v83
	s_waitcnt lgkmcnt(10)
	v_mfma_f32_16x16x32_bf16 v[8:11], v[208:211], v[188:191], v[8:11]
	v_exp_f32_e32 v84, v84
	v_mfma_f32_16x16x32_bf16 v[40:43], v[208:211], v[196:199], v[40:43]
	ds_read_b128 v[208:211], v172 offset:57344
	v_exp_f32_e32 v85, v85
	v_mfma_f32_16x16x32_bf16 v[12:15], v[212:215], v[188:191], v[12:15]
	v_exp_f32_e32 v86, v86
	v_mfma_f32_16x16x32_bf16 v[44:47], v[212:215], v[196:199], v[44:47]
	ds_read_b128 v[212:215], v172 offset:61440
	v_exp_f32_e32 v87, v87
	s_waitcnt lgkmcnt(8)
	v_mfma_f32_16x16x32_bf16 v[16:19], v[230:233], v[188:191], v[16:19]
	v_exp_f32_e32 v88, v88
	v_mfma_f32_16x16x32_bf16 v[48:51], v[230:233], v[196:199], v[48:51]
	ds_read_b128 v[230:233], v173 offset:49152
	v_exp_f32_e32 v89, v89
	v_mfma_f32_16x16x32_bf16 v[20:23], v[234:237], v[188:191], v[20:23]
	v_exp_f32_e32 v90, v90
	v_mfma_f32_16x16x32_bf16 v[52:55], v[234:237], v[196:199], v[52:55]
	ds_read_b128 v[234:237], v173 offset:53248
	v_exp_f32_e32 v91, v91
	s_waitcnt lgkmcnt(5)
	v_mfma_f32_16x16x32_bf16 v[24:27], v[238:241], v[188:191], v[24:27]
	v_exp_f32_e32 v92, v92
	v_mfma_f32_16x16x32_bf16 v[56:59], v[238:241], v[196:199], v[56:59]
	ds_read_b128 v[238:241], v173 offset:57344
	v_exp_f32_e32 v93, v93
	v_mfma_f32_16x16x32_bf16 v[28:31], v[242:245], v[188:191], v[28:31]
	v_exp_f32_e32 v94, v94
	v_mfma_f32_16x16x32_bf16 v[60:63], v[242:245], v[196:199], v[60:63]
	ds_read_b128 v[242:245], v173 offset:61440
	v_exp_f32_e32 v95, v95
	s_waitcnt vmcnt(2)
	s_barrier
; __device__ __forceinline__ void partialSM(f32x16& p0, f32x16& p1, float& m_reg, float& mn, float& alpha) {
;     ...
;   for (int r = 0; r < 16; ++r) p0[r] = __builtin_amdgcn_exp2f(p0[r]);
; }
; __device__ __forceinline__ void finishSM(f32x16& p0, f32x16& p1, float alpha, float& l_reg, bf16x8& pa0, bf16x8& pa1, bf16x8& pa2, bf16x8& pa3) {
; #pragma unroll
;   for (int r = 0; r < 16; ++r) p1[r] = __builtin_amdgcn_exp2f(p1[r]);
;   float ps = 0;
; #pragma unroll
;   for (int r = 0; r < 16; ++r) ps += p0[r];
; #pragma unroll
;   for (int r = 0; r < 16; ++r) ps += p1[r];
;   { auto rr = __builtin_amdgcn_permlane32_swap(__float_as_uint(ps), __float_as_uint(ps), false, false);
;     ps = __uint_as_float(rr[0]) + __uint_as_float(rr[1]); }
;   l_reg = l_reg * alpha + ps;
;     ...
;   PK4(p0, 0, pa0); PK4(p0, 8, pa1); PK4(p1, 0, pa2); PK4(p1, 8, pa3);
;     ...
; }
; __device__ __forceinline__ void qkt(f32x16& p0, f32x16& p1, const bf16* Ks, const bf16x8* qr, int r32, int hi) {
;   p0 = f32x16{}; p1 = f32x16{};
; #pragma unroll
;   for (int d0 = 0; d0 < 8; ++d0) { int cb = (d0 * 16 + hi * 8) * 2;
;     bf16x8 b0 = *reinterpret_cast<const bf16x8*>((const char*)Ks + KSWZ(r32, cb));
;     bf16x8 b1 = *reinterpret_cast<const bf16x8*>((const char*)Ks + KSWZ(32 + r32, cb));
;     p0 = __builtin_amdgcn_mfma_f32_32x32x16_bf16(b0, qr[d0], p0, 0, 0, 0);
;     p1 = __builtin_amdgcn_mfma_f32_32x32x16_bf16(b1, qr[d0], p1, 0, 0, 0); }
; }
; __device__ __forceinline__ int v_st(int k, int c) { const int kk = (k & ~0xC) | ((k & 4) << 1) | ((k & 8) >> 1); return ((kk >> 3) * 4 + (c >> 5)) * 512 + ((kk & 7) * 32 + (c & 31)) * 2; }
; __device__ __forceinline__ int v_rd_base(int lane) { return ((lane & 3) << 3) | (((lane >> 2) & 3) << 6) | (((lane >> 4) & 1) << 5) | (((lane >> 5) & 1) << 8); }
; template <int OFF> __device__ __forceinline__ s16x4 tr_read(int vb) {
;   s16x4 r; asm volatile("ds_read_b64_tr_b16 %0, %1 offset:%2" : "=&v"(r) : "v"(vb), "i"(OFF) : "memory"); return r;
; }
; template <int D0> __device__ __forceinline__ void pv_one(f32x16& od, int vb, bf16x8 pa0, bf16x8 pa1, bf16x8 pa2, bf16x8 pa3) {
;   const s16x4 l0 = tr_read<v_rd_off(D0, 0, 0)>(vb), h0 = tr_read<v_rd_off(D0, 0, 1)>(vb), l1 = tr_read<v_rd_off(D0, 1, 0)>(vb), h1 = tr_read<v_rd_off(D0, 1, 1)>(vb);
	s_waitcnt lgkmcnt(6)
	v_mfma_f32_16x16x32_bf16 v[128:131], v[200:203], v[96:99], 0
	v_add_f32_e32 v169, v169, v64
	v_mfma_f32_16x16x32_bf16 v[132:135], v[200:203], v[112:115], 0
	ds_read_b128 v[200:203], v174 offset:49152
	v_add_f32_e32 v169, v169, v65
	v_cvt_pk_bf16_f32 v184, v64, v65
	v_mfma_f32_16x16x32_bf16 v[136:139], v[204:207], v[96:99], 0
	v_add_f32_e32 v169, v169, v66
	v_mfma_f32_16x16x32_bf16 v[140:143], v[204:207], v[112:115], 0
	ds_read_b128 v[204:207], v174 offset:53248
	v_add_f32_e32 v169, v169, v67
	v_cvt_pk_bf16_f32 v185, v66, v67
	s_waitcnt lgkmcnt(6)
	v_mfma_f32_16x16x32_bf16 v[144:147], v[208:211], v[96:99], 0
	v_add_f32_e32 v222, v222, v68
	v_mfma_f32_16x16x32_bf16 v[148:151], v[208:211], v[112:115], 0
	ds_read_b128 v[208:211], v174 offset:57344
	v_add_f32_e32 v222, v222, v69
	v_cvt_pk_bf16_f32 v186, v72, v73
	v_mfma_f32_16x16x32_bf16 v[152:155], v[212:215], v[96:99], 0
	v_add_f32_e32 v222, v222, v70
	v_mfma_f32_16x16x32_bf16 v[156:159], v[212:215], v[112:115], 0
	ds_read_b128 v[212:215], v174 offset:61440
	v_add_f32_e32 v222, v222, v71
	v_cvt_pk_bf16_f32 v187, v74, v75
	s_waitcnt lgkmcnt(6)
	v_mfma_f32_16x16x32_bf16 v[128:131], v[230:233], v[100:103], v[128:131]
	v_add_f32_e32 v169, v169, v72
	v_mfma_f32_16x16x32_bf16 v[132:135], v[230:233], v[116:119], v[132:135]
	ds_read_b128 v[230:233], v175 offset:49152
	v_add_f32_e32 v169, v169, v73
	v_cvt_pk_bf16_f32 v188, v80, v81
	v_mfma_f32_16x16x32_bf16 v[136:139], v[234:237], v[100:103], v[136:139]
	v_add_f32_e32 v169, v169, v74
	v_mfma_f32_16x16x32_bf16 v[140:143], v[234:237], v[116:119], v[140:143]
	ds_read_b128 v[234:237], v175 offset:53248
	v_add_f32_e32 v169, v169, v75
	v_cvt_pk_bf16_f32 v189, v82, v83
	s_waitcnt lgkmcnt(6)
	v_mfma_f32_16x16x32_bf16 v[144:147], v[238:241], v[100:103], v[144:147]
	v_add_f32_e32 v222, v222, v76
	v_mfma_f32_16x16x32_bf16 v[148:151], v[238:241], v[116:119], v[148:151]
	ds_read_b128 v[238:241], v175 offset:57344
	v_add_f32_e32 v222, v222, v77
	v_cvt_pk_bf16_f32 v190, v88, v89
	v_mfma_f32_16x16x32_bf16 v[152:155], v[242:245], v[100:103], v[152:155]
	v_add_f32_e32 v222, v222, v78
	v_mfma_f32_16x16x32_bf16 v[156:159], v[242:245], v[116:119], v[156:159]
	ds_read_b128 v[242:245], v175 offset:61440
	v_add_f32_e32 v222, v222, v79
	v_cvt_pk_bf16_f32 v191, v90, v91
	s_waitcnt lgkmcnt(6)
	v_mfma_f32_16x16x32_bf16 v[128:131], v[200:203], v[104:107], v[128:131]
	v_add_f32_e32 v169, v169, v80
	v_mfma_f32_16x16x32_bf16 v[132:135], v[200:203], v[120:123], v[132:135]
	v_add_f32_e32 v169, v169, v81
	v_cvt_pk_bf16_f32 v192, v68, v69
	v_mfma_f32_16x16x32_bf16 v[136:139], v[204:207], v[104:107], v[136:139]
	v_add_f32_e32 v169, v169, v82
	v_mfma_f32_16x16x32_bf16 v[140:143], v[204:207], v[120:123], v[140:143]
	v_add_f32_e32 v169, v169, v83
	v_cvt_pk_bf16_f32 v193, v70, v71
	s_waitcnt lgkmcnt(4)
	v_mfma_f32_16x16x32_bf16 v[144:147], v[208:211], v[104:107], v[144:147]
	ds_read_b64_tr_b16 v[200:201], v176 offset:32768
	ds_read_b64_tr_b16 v[202:203], v176 offset:36864
	v_add_f32_e32 v222, v222, v84
	v_mfma_f32_16x16x32_bf16 v[148:151], v[208:211], v[120:123], v[148:151]
	v_add_f32_e32 v222, v222, v85
	v_cvt_pk_bf16_f32 v194, v76, v77
	v_mfma_f32_16x16x32_bf16 v[152:155], v[212:215], v[104:107], v[152:155]
	ds_read_b64_tr_b16 v[204:205], v177 offset:32768
	ds_read_b64_tr_b16 v[206:207], v177 offset:36864
	v_add_f32_e32 v222, v222, v86
	v_mfma_f32_16x16x32_bf16 v[156:159], v[212:215], v[120:123], v[156:159]
	v_add_f32_e32 v222, v222, v87
	v_cvt_pk_bf16_f32 v195, v78, v79
	s_waitcnt lgkmcnt(6)
	v_mfma_f32_16x16x32_bf16 v[128:131], v[230:233], v[108:111], v[128:131]
	ds_read_b64_tr_b16 v[208:209], v178 offset:32768
	ds_read_b64_tr_b16 v[210:211], v178 offset:36864
	v_add_f32_e32 v169, v169, v88
	v_mfma_f32_16x16x32_bf16 v[132:135], v[230:233], v[124:127], v[132:135]
	v_add_f32_e32 v169, v169, v89
	v_cvt_pk_bf16_f32 v196, v84, v85
	v_mfma_f32_16x16x32_bf16 v[136:139], v[234:237], v[108:111], v[136:139]
	ds_read_b64_tr_b16 v[212:213], v179 offset:32768
	ds_read_b64_tr_b16 v[214:215], v179 offset:36864
	v_add_f32_e32 v169, v169, v90
	v_mfma_f32_16x16x32_bf16 v[140:143], v[234:237], v[124:127], v[140:143]
	v_add_f32_e32 v169, v169, v91
	v_cvt_pk_bf16_f32 v197, v86, v87
	s_waitcnt lgkmcnt(8)
	v_mfma_f32_16x16x32_bf16 v[144:147], v[238:241], v[108:111], v[144:147]
	ds_read_b64_tr_b16 v[230:231], v180 offset:32768
	ds_read_b64_tr_b16 v[232:233], v180 offset:36864
	v_add_f32_e32 v222, v222, v92
	v_mfma_f32_16x16x32_bf16 v[148:151], v[238:241], v[124:127], v[148:151]
	v_add_f32_e32 v222, v222, v93
	v_cvt_pk_bf16_f32 v198, v92, v93
	v_mfma_f32_16x16x32_bf16 v[152:155], v[242:245], v[108:111], v[152:155]
	ds_read_b64_tr_b16 v[234:235], v182 offset:32768
	ds_read_b64_tr_b16 v[236:237], v182 offset:36864
	v_add_f32_e32 v222, v222, v94
	v_mfma_f32_16x16x32_bf16 v[156:159], v[242:245], v[124:127], v[156:159]
	v_add_f32_e32 v222, v222, v95
	v_cvt_pk_bf16_f32 v199, v94, v95
	s_waitcnt lgkmcnt(8)
	v_mfma_f32_16x16x32_bf16 v[0:3], v[200:203], v[184:187], v[0:3]
	v_exp_f32_e32 v128, v128
	v_mfma_f32_16x16x32_bf16 v[32:35], v[200:203], v[192:195], v[32:35]
	ds_read_b64_tr_b16 v[238:239], v216 offset:32768
	ds_read_b64_tr_b16 v[240:241], v216 offset:36864
	v_exp_f32_e32 v129, v129
	v_mfma_f32_16x16x32_bf16 v[4:7], v[204:207], v[184:187], v[4:7]
	v_exp_f32_e32 v130, v130
	v_mfma_f32_16x16x32_bf16 v[36:39], v[204:207], v[192:195], v[36:39]
	ds_read_b64_tr_b16 v[242:243], v217 offset:32768
	ds_read_b64_tr_b16 v[244:245], v217 offset:36864
	v_exp_f32_e32 v131, v131
	s_waitcnt lgkmcnt(8)
; __device__ __forceinline__ void partialSM(f32x16& p0, f32x16& p1, float& m_reg, float& mn, float& alpha) {
;     ...
;   for (int r = 0; r < 16; ++r) p0[r] = __builtin_amdgcn_exp2f(p0[r]);
; }
; __device__ __forceinline__ void finishSM(f32x16& p0, f32x16& p1, float alpha, float& l_reg, bf16x8& pa0, bf16x8& pa1, bf16x8& pa2, bf16x8& pa3) {
; #pragma unroll
;   for (int r = 0; r < 16; ++r) p1[r] = __builtin_amdgcn_exp2f(p1[r]);
;   float ps = 0;
; #pragma unroll
;   for (int r = 0; r < 16; ++r) ps += p0[r];
; #pragma unroll
;   for (int r = 0; r < 16; ++r) ps += p1[r];
;   { auto rr = __builtin_amdgcn_permlane32_swap(__float_as_uint(ps), __float_as_uint(ps), false, false);
;     ps = __uint_as_float(rr[0]) + __uint_as_float(rr[1]); }
;   l_reg = l_reg * alpha + ps;
;     ...
;   PK4(p0, 0, pa0); PK4(p0, 8, pa1); PK4(p1, 0, pa2); PK4(p1, 8, pa3);
;     ...
; }
; __device__ __forceinline__ void qkt(f32x16& p0, f32x16& p1, const bf16* Ks, const bf16x8* qr, int r32, int hi) {
;   p0 = f32x16{}; p1 = f32x16{};
; #pragma unroll
;   for (int d0 = 0; d0 < 8; ++d0) { int cb = (d0 * 16 + hi * 8) * 2;
;     bf16x8 b0 = *reinterpret_cast<const bf16x8*>((const char*)Ks + KSWZ(r32, cb));
;     bf16x8 b1 = *reinterpret_cast<const bf16x8*>((const char*)Ks + KSWZ(32 + r32, cb));
;     p0 = __builtin_amdgcn_mfma_f32_32x32x16_bf16(b0, qr[d0], p0, 0, 0, 0);
;     p1 = __builtin_amdgcn_mfma_f32_32x32x16_bf16(b1, qr[d0], p1, 0, 0, 0); }
; }
; __device__ __forceinline__ int v_st(int k, int c) { const int kk = (k & ~0xC) | ((k & 4) << 1) | ((k & 8) >> 1); return ((kk >> 3) * 4 + (c >> 5)) * 512 + ((kk & 7) * 32 + (c & 31)) * 2; }
; __device__ __forceinline__ int v_rd_base(int lane) { return ((lane & 3) << 3) | (((lane >> 2) & 3) << 6) | (((lane >> 4) & 1) << 5) | (((lane >> 5) & 1) << 8); }
; template <int OFF> __device__ __forceinline__ s16x4 tr_read(int vb) {
;   s16x4 r; asm volatile("ds_read_b64_tr_b16 %0, %1 offset:%2" : "=&v"(r) : "v"(vb), "i"(OFF) : "memory"); return r;
; }
; template <int D0> __device__ __forceinline__ void pv_one(f32x16& od, int vb, bf16x8 pa0, bf16x8 pa1, bf16x8 pa2, bf16x8 pa3) {
;   const s16x4 l0 = tr_read<v_rd_off(D0, 0, 0)>(vb), h0 = tr_read<v_rd_off(D0, 0, 1)>(vb), l1 = tr_read<v_rd_off(D0, 1, 0)>(vb), h1 = tr_read<v_rd_off(D0, 1, 1)>(vb);
	v_mfma_f32_16x16x32_bf16 v[8:11], v[208:211], v[184:187], v[8:11]
	v_exp_f32_e32 v132, v132
	v_mfma_f32_16x16x32_bf16 v[40:43], v[208:211], v[192:195], v[40:43]
	ds_read_b64_tr_b16 v[200:201], v176 offset:40960
	ds_read_b64_tr_b16 v[202:203], v176 offset:45056
	v_exp_f32_e32 v133, v133
	v_mfma_f32_16x16x32_bf16 v[12:15], v[212:215], v[184:187], v[12:15]
	v_exp_f32_e32 v134, v134
	v_mfma_f32_16x16x32_bf16 v[44:47], v[212:215], v[192:195], v[44:47]
	ds_read_b64_tr_b16 v[204:205], v177 offset:40960
	ds_read_b64_tr_b16 v[206:207], v177 offset:45056
	v_exp_f32_e32 v135, v135
	s_waitcnt lgkmcnt(8)
	v_mfma_f32_16x16x32_bf16 v[16:19], v[230:233], v[184:187], v[16:19]
	v_exp_f32_e32 v136, v136
	v_mfma_f32_16x16x32_bf16 v[48:51], v[230:233], v[192:195], v[48:51]
	ds_read_b64_tr_b16 v[208:209], v178 offset:40960
	ds_read_b64_tr_b16 v[210:211], v178 offset:45056
	v_exp_f32_e32 v137, v137
	v_mfma_f32_16x16x32_bf16 v[20:23], v[234:237], v[184:187], v[20:23]
	v_exp_f32_e32 v138, v138
	v_mfma_f32_16x16x32_bf16 v[52:55], v[234:237], v[192:195], v[52:55]
	ds_read_b64_tr_b16 v[212:213], v179 offset:40960
	ds_read_b64_tr_b16 v[214:215], v179 offset:45056
	v_exp_f32_e32 v139, v139
	s_waitcnt lgkmcnt(8)
	v_mfma_f32_16x16x32_bf16 v[24:27], v[238:241], v[184:187], v[24:27]
	v_exp_f32_e32 v140, v140
	v_mfma_f32_16x16x32_bf16 v[56:59], v[238:241], v[192:195], v[56:59]
	ds_read_b64_tr_b16 v[230:231], v180 offset:40960
	ds_read_b64_tr_b16 v[232:233], v180 offset:45056
	v_exp_f32_e32 v141, v141
	v_mfma_f32_16x16x32_bf16 v[28:31], v[242:245], v[184:187], v[28:31]
	v_exp_f32_e32 v142, v142
	v_mfma_f32_16x16x32_bf16 v[60:63], v[242:245], v[192:195], v[60:63]
	ds_read_b64_tr_b16 v[234:235], v182 offset:40960
	ds_read_b64_tr_b16 v[236:237], v182 offset:45056
	v_exp_f32_e32 v143, v143
	s_waitcnt lgkmcnt(8)
	v_mfma_f32_16x16x32_bf16 v[0:3], v[200:203], v[188:191], v[0:3]
	v_exp_f32_e32 v144, v144
	v_mfma_f32_16x16x32_bf16 v[32:35], v[200:203], v[196:199], v[32:35]
	ds_read_b64_tr_b16 v[238:239], v216 offset:40960
	ds_read_b64_tr_b16 v[240:241], v216 offset:45056
	v_exp_f32_e32 v145, v145
	v_mfma_f32_16x16x32_bf16 v[4:7], v[204:207], v[188:191], v[4:7]
	v_exp_f32_e32 v146, v146
	v_mfma_f32_16x16x32_bf16 v[36:39], v[204:207], v[196:199], v[36:39]
	ds_read_b64_tr_b16 v[242:243], v217 offset:40960
	ds_read_b64_tr_b16 v[244:245], v217 offset:45056
	v_exp_f32_e32 v147, v147
	s_waitcnt lgkmcnt(8)
	v_mfma_f32_16x16x32_bf16 v[8:11], v[208:211], v[188:191], v[8:11]
	v_exp_f32_e32 v148, v148
	v_mfma_f32_16x16x32_bf16 v[40:43], v[208:211], v[196:199], v[40:43]
	v_exp_f32_e32 v149, v149
	v_mfma_f32_16x16x32_bf16 v[12:15], v[212:215], v[188:191], v[12:15]
	v_exp_f32_e32 v150, v150
	v_mfma_f32_16x16x32_bf16 v[44:47], v[212:215], v[196:199], v[44:47]
	v_exp_f32_e32 v151, v151
	s_waitcnt lgkmcnt(4)
	v_mfma_f32_16x16x32_bf16 v[16:19], v[230:233], v[188:191], v[16:19]
	v_exp_f32_e32 v152, v152
	v_mfma_f32_16x16x32_bf16 v[48:51], v[230:233], v[196:199], v[48:51]
	v_exp_f32_e32 v153, v153
	v_mfma_f32_16x16x32_bf16 v[20:23], v[234:237], v[188:191], v[20:23]
	v_exp_f32_e32 v154, v154
	v_mfma_f32_16x16x32_bf16 v[52:55], v[234:237], v[196:199], v[52:55]
	v_exp_f32_e32 v155, v155
	s_waitcnt lgkmcnt(0)
	v_mfma_f32_16x16x32_bf16 v[24:27], v[238:241], v[188:191], v[24:27]
	v_exp_f32_e32 v156, v156
	v_mfma_f32_16x16x32_bf16 v[56:59], v[238:241], v[196:199], v[56:59]
	v_exp_f32_e32 v157, v157
	v_mfma_f32_16x16x32_bf16 v[28:31], v[242:245], v[188:191], v[28:31]
	v_exp_f32_e32 v158, v158
	v_mfma_f32_16x16x32_bf16 v[60:63], v[242:245], v[196:199], v[60:63]
	v_exp_f32_e32 v159, v159
	s_waitcnt lgkmcnt(0)
	s_waitcnt vmcnt(0)
	s_barrier
	v_add_f32_e32 v169, v169, v128
	v_add_f32_e32 v169, v169, v129
	v_cvt_pk_bf16_f32 v184, v128, v129
	v_add_f32_e32 v169, v169, v130
	v_add_f32_e32 v169, v169, v131
	v_cvt_pk_bf16_f32 v185, v130, v131
	v_add_f32_e32 v222, v222, v132
	v_add_f32_e32 v222, v222, v133
	v_cvt_pk_bf16_f32 v186, v136, v137
	v_add_f32_e32 v222, v222, v134
	v_add_f32_e32 v222, v222, v135
	v_cvt_pk_bf16_f32 v187, v138, v139
	v_add_f32_e32 v169, v169, v136
	v_add_f32_e32 v169, v169, v137
	v_cvt_pk_bf16_f32 v188, v144, v145
	v_add_f32_e32 v169, v169, v138
	v_add_f32_e32 v169, v169, v139
	v_cvt_pk_bf16_f32 v189, v146, v147
	v_add_f32_e32 v222, v222, v140
	v_add_f32_e32 v222, v222, v141
	v_cvt_pk_bf16_f32 v190, v152, v153
	v_add_f32_e32 v222, v222, v142
	v_add_f32_e32 v222, v222, v143
	v_cvt_pk_bf16_f32 v191, v154, v155
	v_add_f32_e32 v169, v169, v144
	v_add_f32_e32 v169, v169, v145
	v_cvt_pk_bf16_f32 v192, v132, v133
	v_add_f32_e32 v169, v169, v146
	v_add_f32_e32 v169, v169, v147
	v_cvt_pk_bf16_f32 v193, v134, v135
	ds_read_b64_tr_b16 v[200:201], v176 offset:49152
	ds_read_b64_tr_b16 v[202:203], v176 offset:53248
	v_add_f32_e32 v222, v222, v148
	v_add_f32_e32 v222, v222, v149
	v_cvt_pk_bf16_f32 v194, v140, v141
	ds_read_b64_tr_b16 v[204:205], v177 offset:49152
	ds_read_b64_tr_b16 v[206:207], v177 offset:53248
	v_add_f32_e32 v222, v222, v150
	v_add_f32_e32 v222, v222, v151
	v_cvt_pk_bf16_f32 v195, v142, v143
	ds_read_b64_tr_b16 v[208:209], v178 offset:49152
	ds_read_b64_tr_b16 v[210:211], v178 offset:53248
	v_add_f32_e32 v169, v169, v152
	v_add_f32_e32 v169, v169, v153
	v_cvt_pk_bf16_f32 v196, v148, v149
	ds_read_b64_tr_b16 v[212:213], v179 offset:49152
	ds_read_b64_tr_b16 v[214:215], v179 offset:53248
	v_add_f32_e32 v169, v169, v154
	v_add_f32_e32 v169, v169, v155
	v_cvt_pk_bf16_f32 v197, v150, v151
	ds_read_b64_tr_b16 v[230:231], v180 offset:49152
	ds_read_b64_tr_b16 v[232:233], v180 offset:53248
	v_add_f32_e32 v222, v222, v156
	v_add_f32_e32 v222, v222, v157
	v_cvt_pk_bf16_f32 v198, v156, v157
	ds_read_b64_tr_b16 v[234:235], v182 offset:49152
	ds_read_b64_tr_b16 v[236:237], v182 offset:53248
	v_add_f32_e32 v222, v222, v158
	v_add_f32_e32 v222, v222, v159
	v_cvt_pk_bf16_f32 v199, v158, v159
	s_waitcnt lgkmcnt(8)
; #define SBAR() __builtin_amdgcn_sched_barrier(0)
; template <int OFF> __device__ __forceinline__ s16x4 tr_read(int vb) {
;   s16x4 r; asm volatile("ds_read_b64_tr_b16 %0, %1 offset:%2" : "=&v"(r) : "v"(vb), "i"(OFF) : "memory"); return r;
; }
; template <int D0> __device__ __forceinline__ void pv_one(f32x16& od, int vb, bf16x8 pa0, bf16x8 pa1, bf16x8 pa2, bf16x8 pa3) {
;   const s16x4 l0 = tr_read<v_rd_off(D0, 0, 0)>(vb), h0 = tr_read<v_rd_off(D0, 0, 1)>(vb), l1 = tr_read<v_rd_off(D0, 1, 0)>(vb), h1 = tr_read<v_rd_off(D0, 1, 1)>(vb);
;   const s16x4 l2 = tr_read<v_rd_off(D0, 2, 0)>(vb), h2 = tr_read<v_rd_off(D0, 2, 1)>(vb), l3 = tr_read<v_rd_off(D0, 3, 0)>(vb), h3 = tr_read<v_rd_off(D0, 3, 1)>(vb);
;   asm volatile("s_waitcnt lgkmcnt(0)" ::: "memory"); SBAR();
;     ...
;   od = __builtin_amdgcn_mfma_f32_32x32x16_bf16(pa0, PK(l0, h0), od, 0, 0, 0);
;   od = __builtin_amdgcn_mfma_f32_32x32x16_bf16(pa1, PK(l1, h1), od, 0, 0, 0);
;   od = __builtin_amdgcn_mfma_f32_32x32x16_bf16(pa2, PK(l2, h2), od, 0, 0, 0);
;   od = __builtin_amdgcn_mfma_f32_32x32x16_bf16(pa3, PK(l3, h3), od, 0, 0, 0);
;     ...
; }
; __device__ __forceinline__ void pv_d0(f32x16* o, int vb, bf16x8 pa0, bf16x8 pa1, bf16x8 pa2, bf16x8 pa3) {
;   pv_one<0>(o[0], vb, pa0, pa1, pa2, pa3); pv_one<1>(o[1], vb, pa0, pa1, pa2, pa3); pv_one<2>(o[2], vb, pa0, pa1, pa2, pa3); pv_one<3>(o[3], vb, pa0, pa1, pa2, pa3);
	v_mfma_f32_16x16x32_bf16 v[0:3], v[200:203], v[184:187], v[0:3]
	v_mfma_f32_16x16x32_bf16 v[32:35], v[200:203], v[192:195], v[32:35]
	ds_read_b64_tr_b16 v[238:239], v216 offset:49152
	ds_read_b64_tr_b16 v[240:241], v216 offset:53248
	v_mfma_f32_16x16x32_bf16 v[4:7], v[204:207], v[184:187], v[4:7]
	v_mfma_f32_16x16x32_bf16 v[36:39], v[204:207], v[192:195], v[36:39]
	ds_read_b64_tr_b16 v[242:243], v217 offset:49152
	ds_read_b64_tr_b16 v[244:245], v217 offset:53248
	s_waitcnt lgkmcnt(8)
	v_mfma_f32_16x16x32_bf16 v[8:11], v[208:211], v[184:187], v[8:11]
	v_mfma_f32_16x16x32_bf16 v[40:43], v[208:211], v[192:195], v[40:43]
	ds_read_b64_tr_b16 v[200:201], v176 offset:57344
	ds_read_b64_tr_b16 v[202:203], v176 offset:61440
	v_mfma_f32_16x16x32_bf16 v[12:15], v[212:215], v[184:187], v[12:15]
	v_mfma_f32_16x16x32_bf16 v[44:47], v[212:215], v[192:195], v[44:47]
	ds_read_b64_tr_b16 v[204:205], v177 offset:57344
	ds_read_b64_tr_b16 v[206:207], v177 offset:61440
	s_waitcnt lgkmcnt(8)
	v_mfma_f32_16x16x32_bf16 v[16:19], v[230:233], v[184:187], v[16:19]
	v_mfma_f32_16x16x32_bf16 v[48:51], v[230:233], v[192:195], v[48:51]
	ds_read_b64_tr_b16 v[208:209], v178 offset:57344
	ds_read_b64_tr_b16 v[210:211], v178 offset:61440
	v_mfma_f32_16x16x32_bf16 v[20:23], v[234:237], v[184:187], v[20:23]
	v_mfma_f32_16x16x32_bf16 v[52:55], v[234:237], v[192:195], v[52:55]
	ds_read_b64_tr_b16 v[212:213], v179 offset:57344
	ds_read_b64_tr_b16 v[214:215], v179 offset:61440
	s_waitcnt lgkmcnt(8)
	v_mfma_f32_16x16x32_bf16 v[24:27], v[238:241], v[184:187], v[24:27]
	v_mfma_f32_16x16x32_bf16 v[56:59], v[238:241], v[192:195], v[56:59]
	ds_read_b64_tr_b16 v[230:231], v180 offset:57344
	ds_read_b64_tr_b16 v[232:233], v180 offset:61440
	v_mfma_f32_16x16x32_bf16 v[28:31], v[242:245], v[184:187], v[28:31]
	v_mfma_f32_16x16x32_bf16 v[60:63], v[242:245], v[192:195], v[60:63]
	ds_read_b64_tr_b16 v[234:235], v182 offset:57344
	ds_read_b64_tr_b16 v[236:237], v182 offset:61440
	s_waitcnt lgkmcnt(8)
	v_mfma_f32_16x16x32_bf16 v[0:3], v[200:203], v[188:191], v[0:3]
	v_mfma_f32_16x16x32_bf16 v[32:35], v[200:203], v[196:199], v[32:35]
	ds_read_b64_tr_b16 v[238:239], v216 offset:57344
	ds_read_b64_tr_b16 v[240:241], v216 offset:61440
	v_mfma_f32_16x16x32_bf16 v[4:7], v[204:207], v[188:191], v[4:7]
	v_mfma_f32_16x16x32_bf16 v[36:39], v[204:207], v[196:199], v[36:39]
	ds_read_b64_tr_b16 v[242:243], v217 offset:57344
	ds_read_b64_tr_b16 v[244:245], v217 offset:61440
	s_waitcnt lgkmcnt(8)
	v_mfma_f32_16x16x32_bf16 v[8:11], v[208:211], v[188:191], v[8:11]
	v_mfma_f32_16x16x32_bf16 v[40:43], v[208:211], v[196:199], v[40:43]
	v_mfma_f32_16x16x32_bf16 v[12:15], v[212:215], v[188:191], v[12:15]
	v_mfma_f32_16x16x32_bf16 v[44:47], v[212:215], v[196:199], v[44:47]
	s_waitcnt lgkmcnt(4)
	v_mfma_f32_16x16x32_bf16 v[16:19], v[230:233], v[188:191], v[16:19]
	v_mfma_f32_16x16x32_bf16 v[48:51], v[230:233], v[196:199], v[48:51]
	v_mfma_f32_16x16x32_bf16 v[20:23], v[234:237], v[188:191], v[20:23]
	v_mfma_f32_16x16x32_bf16 v[52:55], v[234:237], v[196:199], v[52:55]
	s_waitcnt lgkmcnt(0)
	v_mfma_f32_16x16x32_bf16 v[24:27], v[238:241], v[188:191], v[24:27]
	v_mfma_f32_16x16x32_bf16 v[56:59], v[238:241], v[196:199], v[56:59]
	v_mfma_f32_16x16x32_bf16 v[28:31], v[242:245], v[188:191], v[28:31]
	v_mfma_f32_16x16x32_bf16 v[60:63], v[242:245], v[196:199], v[60:63]
	s_waitcnt lgkmcnt(0)
	s_waitcnt vmcnt(0)
	s_barrier
; __device__ __forceinline__ int crow(int r, int hi) { return (r & 3) + 8 * (r >> 2) + 4 * hi; }
;     ...
;   if (hi == 0) li_l[r32] = l_reg; asm volatile("s_waitcnt lgkmcnt(0)" ::: "memory");
;   if constexpr (MODE == 1) { if (hi == 0) lse_out[(long)(wid * QBLK + r32) * lse_stride] = m_reg * SCALE + __logf(l_reg); }
;   float rli[16];
; #pragma unroll
;   for (int r = 0; r < 16; ++r) rli[r] = __builtin_amdgcn_rcpf(li_l[crow(r, hi)]);
;   bf16* Ow = Ob + (long)(wid * QBLK) * ldo;
; #pragma unroll
;   for (int r = 0; r < 16; ++r) { const int orow = crow(r, hi);
; #pragma unroll
;     for (int d0 = 0; d0 < 4; ++d0) Ow[(long)orow * ldo + d0 * 32 + r32] = __float2bfloat16(o[d0][r] * rli[r]); }
;   __syncthreads();
	s_setprio 0
	v_and_b32_e32 v64, 63, v218
	v_lshlrev_b32_e32 v64, 2, v64
	v_xor_b32_e32 v65, 64, v64
	v_xor_b32_e32 v66, 0x80, v64
	ds_bpermute_b32 v67, v65, v169
	s_waitcnt lgkmcnt(0)
	v_add_f32_e32 v169, v169, v67
	ds_bpermute_b32 v67, v66, v169
	s_waitcnt lgkmcnt(0)
	v_add_f32_e32 v169, v169, v67
	v_rcp_f32_e32 v169, v169
	ds_bpermute_b32 v67, v65, v222
	s_waitcnt lgkmcnt(0)
	v_add_f32_e32 v222, v222, v67
	ds_bpermute_b32 v67, v66, v222
	s_waitcnt lgkmcnt(0)
	v_add_f32_e32 v222, v222, v67
	v_rcp_f32_e32 v222, v222
	s_lshl_b64 s[0:1], s[20:21], 12
	s_add_u32 s0, s24, s0
	s_addc_u32 s1, s25, s1
	s_lshl_b32 s2, s14, 1
	s_add_u32 s2, s0, s2
	s_addc_u32 s3, s1, 0
	s_ashr_i32 s39, s38, 31
	s_lshl_b64 s[0:1], s[38:39], 12
	s_add_u32 s0, s2, s0
	s_addc_u32 s1, s3, s1
	v_and_b32_e32 v64, 63, v218
	v_and_b32_e32 v65, 15, v64
	v_lshrrev_b32_e32 v66, 4, v64
	v_lshlrev_b32_e32 v66, 3, v66
	v_lshl_or_b32 v68, v65, 12, v66
	v_add_u32_e32 v69, 0x10000, v68
	v_mul_f32_e32 v0, v0, v169
	v_mul_f32_e32 v1, v1, v169
	v_mul_f32_e32 v2, v2, v169
	v_mul_f32_e32 v3, v3, v169
	v_cvt_pk_bf16_f32 v130, v0, v1
	v_cvt_pk_bf16_f32 v131, v2, v3
	global_store_dwordx2 v68, v[130:131], s[0:1] offset:0
	v_mul_f32_e32 v4, v4, v169
	v_mul_f32_e32 v5, v5, v169
	v_mul_f32_e32 v6, v6, v169
	v_mul_f32_e32 v7, v7, v169
	v_cvt_pk_bf16_f32 v132, v4, v5
	v_cvt_pk_bf16_f32 v133, v6, v7
	global_store_dwordx2 v68, v[132:133], s[0:1] offset:32
	v_mul_f32_e32 v8, v8, v169
	v_mul_f32_e32 v9, v9, v169
	v_mul_f32_e32 v10, v10, v169
	v_mul_f32_e32 v11, v11, v169
	v_cvt_pk_bf16_f32 v134, v8, v9
	v_cvt_pk_bf16_f32 v135, v10, v11
	global_store_dwordx2 v68, v[134:135], s[0:1] offset:64
	v_mul_f32_e32 v12, v12, v169
	v_mul_f32_e32 v13, v13, v169
	v_mul_f32_e32 v14, v14, v169
	v_mul_f32_e32 v15, v15, v169
	v_cvt_pk_bf16_f32 v136, v12, v13
	v_cvt_pk_bf16_f32 v137, v14, v15
	global_store_dwordx2 v68, v[136:137], s[0:1] offset:96
	v_mul_f32_e32 v16, v16, v169
	v_mul_f32_e32 v17, v17, v169
	v_mul_f32_e32 v18, v18, v169
	v_mul_f32_e32 v19, v19, v169
	v_cvt_pk_bf16_f32 v138, v16, v17
	v_cvt_pk_bf16_f32 v139, v18, v19
	global_store_dwordx2 v68, v[138:139], s[0:1] offset:128
	v_mul_f32_e32 v20, v20, v169
	v_mul_f32_e32 v21, v21, v169
	v_mul_f32_e32 v22, v22, v169
	v_mul_f32_e32 v23, v23, v169
	v_cvt_pk_bf16_f32 v140, v20, v21
	v_cvt_pk_bf16_f32 v141, v22, v23
	global_store_dwordx2 v68, v[140:141], s[0:1] offset:160
	v_mul_f32_e32 v24, v24, v169
	v_mul_f32_e32 v25, v25, v169
	v_mul_f32_e32 v26, v26, v169
	v_mul_f32_e32 v27, v27, v169
	v_cvt_pk_bf16_f32 v142, v24, v25
	v_cvt_pk_bf16_f32 v143, v26, v27
	global_store_dwordx2 v68, v[142:143], s[0:1] offset:192
	v_mul_f32_e32 v28, v28, v169
	v_mul_f32_e32 v29, v29, v169
	v_mul_f32_e32 v30, v30, v169
	v_mul_f32_e32 v31, v31, v169
	v_cvt_pk_bf16_f32 v144, v28, v29
	v_cvt_pk_bf16_f32 v145, v30, v31
	global_store_dwordx2 v68, v[144:145], s[0:1] offset:224
	v_mul_f32_e32 v32, v32, v222
	v_mul_f32_e32 v33, v33, v222
	v_mul_f32_e32 v34, v34, v222
	v_mul_f32_e32 v35, v35, v222
	v_cvt_pk_bf16_f32 v130, v32, v33
	v_cvt_pk_bf16_f32 v131, v34, v35
	global_store_dwordx2 v69, v[130:131], s[0:1] offset:0
	v_mul_f32_e32 v36, v36, v222
	v_mul_f32_e32 v37, v37, v222
	v_mul_f32_e32 v38, v38, v222
	v_mul_f32_e32 v39, v39, v222
	v_cvt_pk_bf16_f32 v132, v36, v37
	v_cvt_pk_bf16_f32 v133, v38, v39
	global_store_dwordx2 v69, v[132:133], s[0:1] offset:32
	v_mul_f32_e32 v40, v40, v222
	v_mul_f32_e32 v41, v41, v222
	v_mul_f32_e32 v42, v42, v222
	v_mul_f32_e32 v43, v43, v222
	v_cvt_pk_bf16_f32 v134, v40, v41
	v_cvt_pk_bf16_f32 v135, v42, v43
	global_store_dwordx2 v69, v[134:135], s[0:1] offset:64
	v_mul_f32_e32 v44, v44, v222
	v_mul_f32_e32 v45, v45, v222
	v_mul_f32_e32 v46, v46, v222
	v_mul_f32_e32 v47, v47, v222
	v_cvt_pk_bf16_f32 v136, v44, v45
	v_cvt_pk_bf16_f32 v137, v46, v47
	global_store_dwordx2 v69, v[136:137], s[0:1] offset:96
	v_mul_f32_e32 v48, v48, v222
	v_mul_f32_e32 v49, v49, v222
	v_mul_f32_e32 v50, v50, v222
	v_mul_f32_e32 v51, v51, v222
	v_cvt_pk_bf16_f32 v138, v48, v49
	v_cvt_pk_bf16_f32 v139, v50, v51
	global_store_dwordx2 v69, v[138:139], s[0:1] offset:128
	v_mul_f32_e32 v52, v52, v222
	v_mul_f32_e32 v53, v53, v222
	v_mul_f32_e32 v54, v54, v222
	v_mul_f32_e32 v55, v55, v222
	v_cvt_pk_bf16_f32 v140, v52, v53
	v_cvt_pk_bf16_f32 v141, v54, v55
	global_store_dwordx2 v69, v[140:141], s[0:1] offset:160
	v_mul_f32_e32 v56, v56, v222
	v_mul_f32_e32 v57, v57, v222
	v_mul_f32_e32 v58, v58, v222
	v_mul_f32_e32 v59, v59, v222
	v_cvt_pk_bf16_f32 v142, v56, v57
	v_cvt_pk_bf16_f32 v143, v58, v59
	global_store_dwordx2 v69, v[142:143], s[0:1] offset:192
	v_mul_f32_e32 v60, v60, v222
	v_mul_f32_e32 v61, v61, v222
	v_mul_f32_e32 v62, v62, v222
	v_mul_f32_e32 v63, v63, v222
	v_cvt_pk_bf16_f32 v144, v60, v61
	v_cvt_pk_bf16_f32 v145, v62, v63
	global_store_dwordx2 v69, v[144:145], s[0:1] offset:224
	v_lshlrev_b32_e32 v164, 4, v229
	v_mov_b32_e32 v165, 0
	s_mov_b32 s50, -1
	s_barrier
	s_branch .LBB0_478
